# attention softmax row-sum: 31-deep serial v_add_f32 chains replaced by v_pk_add_f32 over aligned exp-output pairs (f32 accumulate, two partial sums + final add)
# baseline (speedup 1.0000x reference)
; #define LAS __attribute__((address_space(3)))
; __device__ __forceinline__ void att_qk_exp(const LAS char* kb, const bf16x8 (&qf)[6], float nm, fa::f32x16& n0, fa::f32x16& n1, fa::f32x16& p0, fa::f32x16& p1, float& lsum, bf16x8 (&pf)[4]) {
;     const fa::f32x16 zero = {0.f, 0.f, 0.f, 0.f, 0.f, 0.f, 0.f, 0.f, 0.f, 0.f, 0.f, 0.f, 0.f, 0.f, 0.f, 0.f};
;     bf16x8 kc0 = *(const LAS bf16x8*)kb, kc1 = *(const LAS bf16x8*)(kb + 32 * fa::KP_A);
;     float ps = 0.f, ps2 = 0.f;
; #pragma unroll
;     for (int st = 0; st < 6; ++st) {
;         bf16x8 kn0 = kc0, kn1 = kc1;
;         if (st < 5) { kn0 = *(const LAS bf16x8*)(kb + 32 * (st + 1)); kn1 = *(const LAS bf16x8*)(kb + 32 * fa::KP_A + 32 * (st + 1)); }
;         n0 = __builtin_amdgcn_mfma_f32_32x32x16_bf16(kc0, qf[st], st == 0 ? zero : n0, 0, 0, 0);
;         n1 = __builtin_amdgcn_mfma_f32_32x32x16_bf16(kc1, qf[st], st == 0 ? zero : n1, 0, 0, 0);
;         constexpr int lo[7] = {0, 2, 6, 8, 10, 14, 16};
; #pragma unroll
;         for (int r = lo[st]; r < lo[st + 1]; ++r) {
;             p0[r] = __builtin_amdgcn_exp2f(vadd1(p0[r], nm)); p1[r] = __builtin_amdgcn_exp2f(vadd1(p1[r], nm));
;             ps += p0[r]; ps += p1[r]; }
;         kc0 = kn0; kc1 = kn1;
;         __builtin_amdgcn_sched_barrier(0);
;     }
;     lsum += ps + ps2;
;     pf[0] = fa::pack_p(p0, 0); pf[1] = fa::pack_p(p0, 8); pf[2] = fa::pack_p(p1, 0); pf[3] = fa::pack_p(p1, 8);
; }
; __device__ __forceinline__ void att_exp_pack(fa::f32x16& p0, fa::f32x16& p1, float nm, float& lsum, bf16x8 (&pf)[4]) {
;     float ps = 0.f, ps2 = 0.f;
; #pragma unroll
;     for (int r = 0; r < 16; ++r) { p0[r] = __builtin_amdgcn_exp2f(vadd1(p0[r], nm)); p1[r] = __builtin_amdgcn_exp2f(vadd1(p1[r], nm)); ps += p0[r]; ps += p1[r]; }
;     lsum += ps + ps2;
;     pf[0] = fa::pack_p(p0, 0); pf[1] = fa::pack_p(p0, 8); pf[2] = fa::pack_p(p1, 0); pf[3] = fa::pack_p(p1, 8);
; }
; __device__ __forceinline__ float att_pv_max(fa::f32x16& o0, fa::f32x16& o1, const LAS char* vb, const bf16x8 (&pf)[4], const fa::f32x16& n0, const fa::f32x16& n1) {
;     using namespace fa;
;     float ta = n0[0], tb = n1[0];
;     s16x4 a0 = vtr(vb), a1 = vtr(vb + 512), b0 = vtr(vb + 4096), b1 = vtr(vb + 4096 + 512);
; #pragma unroll
;     for (int ks = 0; ks < 4; ++ks) {
;         s16x4 na0 = a0, na1 = a1, nb0 = b0, nb1 = b1;
.LBB0_1031:
	s_add_i32 s8, s8, 0
	v_add3_u32 v67, s8, v187, v180
	ds_read_b128 v[34:37], v67 offset:21504
	ds_read_b128 v[50:53], v67 offset:28160
	ds_read_b128 v[68:71], v67 offset:21536
	s_waitcnt lgkmcnt(1)
	v_mfma_f32_32x32x16_bf16 v[50:65], v[50:53], v[132:135], v[226:241]
	ds_read_b128 v[72:75], v67 offset:28192
	v_exp_f32_e32 v2, v2
	v_exp_f32_e32 v18, v18
	v_exp_f32_e32 v3, v3
	v_mfma_f32_32x32x16_bf16 v[34:49], v[34:37], v[132:135], v[226:241]
	v_exp_f32_e32 v19, v19
	s_waitcnt lgkmcnt(1)
	v_mfma_f32_32x32x16_bf16 v[34:49], v[68:71], v[136:139], v[34:49]
	ds_read_b128 v[76:79], v67 offset:21568
	ds_read_b128 v[80:83], v67 offset:28224
	s_waitcnt lgkmcnt(2)
	v_mfma_f32_32x32x16_bf16 v[50:65], v[72:75], v[136:139], v[50:65]
	v_exp_f32_e32 v4, v4
	v_exp_f32_e32 v20, v20
	v_exp_f32_e32 v5, v5
	v_exp_f32_e32 v21, v21
	v_exp_f32_e32 v6, v6
	v_exp_f32_e32 v22, v22
	v_exp_f32_e32 v7, v7
	v_exp_f32_e32 v23, v23
	s_waitcnt lgkmcnt(1)
	v_mfma_f32_32x32x16_bf16 v[34:49], v[76:79], v[140:143], v[34:49]
	ds_read_b128 v[68:71], v67 offset:21600
	ds_read_b128 v[72:75], v67 offset:28256
	v_exp_f32_e32 v8, v8
	s_waitcnt lgkmcnt(2)
	v_mfma_f32_32x32x16_bf16 v[50:65], v[80:83], v[140:143], v[50:65]
	v_exp_f32_e32 v24, v24
	v_exp_f32_e32 v9, v9
	v_exp_f32_e32 v25, v25
	s_waitcnt lgkmcnt(1)
	v_mfma_f32_32x32x16_bf16 v[34:49], v[68:71], v[144:147], v[34:49]
	ds_read_b128 v[76:79], v67 offset:21632
	ds_read_b128 v[80:83], v67 offset:28288
	v_exp_f32_e32 v10, v10
	s_waitcnt lgkmcnt(2)
	v_mfma_f32_32x32x16_bf16 v[50:65], v[72:75], v[144:147], v[50:65]
	v_exp_f32_e32 v26, v26
	v_exp_f32_e32 v11, v11
	v_exp_f32_e32 v27, v27
	s_waitcnt lgkmcnt(1)
	v_mfma_f32_32x32x16_bf16 v[34:49], v[76:79], v[148:151], v[34:49]
	ds_read_b128 v[68:71], v67 offset:21664
	ds_read_b128 v[72:75], v67 offset:28320
	s_waitcnt lgkmcnt(2)
	v_mfma_f32_32x32x16_bf16 v[50:65], v[80:83], v[148:151], v[50:65]
	v_exp_f32_e32 v12, v12
	v_exp_f32_e32 v28, v28
	v_exp_f32_e32 v13, v13
	v_exp_f32_e32 v29, v29
	v_exp_f32_e32 v14, v14
	v_exp_f32_e32 v30, v30
	v_exp_f32_e32 v15, v15
	v_exp_f32_e32 v31, v31
	v_pk_add_f32 v[250:251], v[2:3], v[18:19]
	v_pk_add_f32 v[250:251], v[250:251], v[4:5]
	v_pk_add_f32 v[250:251], v[250:251], v[20:21]
	v_pk_add_f32 v[250:251], v[250:251], v[6:7]
	v_pk_add_f32 v[250:251], v[250:251], v[22:23]
	v_pk_add_f32 v[250:251], v[250:251], v[8:9]
	v_pk_add_f32 v[250:251], v[250:251], v[24:25]
	v_pk_add_f32 v[250:251], v[250:251], v[10:11]
	v_pk_add_f32 v[250:251], v[250:251], v[26:27]
	v_pk_add_f32 v[250:251], v[250:251], v[12:13]
	v_pk_add_f32 v[250:251], v[250:251], v[28:29]
	v_exp_f32_e32 v16, v16
	s_waitcnt lgkmcnt(1)
	v_mfma_f32_32x32x16_bf16 v[34:49], v[68:71], v[152:155], v[34:49]
	v_exp_f32_e32 v32, v32
	v_exp_f32_e32 v17, v17
	v_pk_add_f32 v[250:251], v[250:251], v[14:15]
	s_waitcnt lgkmcnt(0)
	v_mfma_f32_32x32x16_bf16 v[50:65], v[72:75], v[152:155], v[50:65]
	v_exp_f32_e32 v33, v33
	v_pk_add_f32 v[250:251], v[250:251], v[30:31]
	v_pk_add_f32 v[250:251], v[250:251], v[16:17]
	v_pk_add_f32 v[250:251], v[250:251], v[32:33]
	v_add_f32_e32 v67, v250, v251
	v_add_u32_e32 v193, s8, v189
	v_cvt_pk_bf16_f32 v68, v2, v3
	v_cvt_pk_bf16_f32 v69, v4, v5
	v_cvt_pk_bf16_f32 v70, v6, v7
	v_cvt_pk_bf16_f32 v71, v8, v9
	v_cvt_pk_bf16_f32 v72, v10, v11
	v_cvt_pk_bf16_f32 v73, v12, v13
	v_cvt_pk_bf16_f32 v74, v14, v15
	v_cvt_pk_bf16_f32 v75, v16, v17
	v_cvt_pk_bf16_f32 v76, v18, v19
	v_cvt_pk_bf16_f32 v77, v20, v21
	v_cvt_pk_bf16_f32 v78, v22, v23
	v_cvt_pk_bf16_f32 v79, v24, v25
	v_cvt_pk_bf16_f32 v196, v26, v27
	v_cvt_pk_bf16_f32 v197, v28, v29
	v_cvt_pk_bf16_f32 v198, v30, v31
	v_cvt_pk_bf16_f32 v199, v32, v33
	ds_read_b64_tr_b16 v[80:81], v193 offset:13312
	ds_read_b64_tr_b16 v[82:83], v193 offset:13824
	ds_read_b64_tr_b16 v[84:85], v193 offset:14336
	ds_read_b64_tr_b16 v[86:87], v193 offset:14848
	s_waitcnt lgkmcnt(2)
	v_mfma_f32_32x32x16_bf16 v[114:129], v[80:83], v[68:71], v[114:129]
	ds_read_b64_tr_b16 v[80:81], v193 offset:17408
	ds_read_b64_tr_b16 v[82:83], v193 offset:17920
	ds_read_b64_tr_b16 v[88:89], v193 offset:18432
	ds_read_b64_tr_b16 v[90:91], v193 offset:18944
	v_add_f32_e32 v192, v66, v67
	s_waitcnt lgkmcnt(2)
	v_mfma_f32_32x32x16_bf16 v[98:113], v[80:83], v[68:71], v[98:113]
	s_waitcnt lgkmcnt(0)
	v_mfma_f32_32x32x16_bf16 v[98:113], v[88:91], v[72:75], v[98:113]
	ds_read_b64_tr_b16 v[66:67], v193 offset:15360
	ds_read_b64_tr_b16 v[68:69], v193 offset:15872
	ds_read_b64_tr_b16 v[80:81], v193 offset:19456
	ds_read_b64_tr_b16 v[82:83], v193 offset:19968
	v_mfma_f32_32x32x16_bf16 v[114:129], v[84:87], v[72:75], v[114:129]
	s_waitcnt lgkmcnt(0)
	v_mfma_f32_32x32x16_bf16 v[98:113], v[80:83], v[76:79], v[98:113]
	ds_read_b64_tr_b16 v[84:85], v193 offset:16384
	ds_read_b64_tr_b16 v[86:87], v193 offset:16896
	ds_read_b64_tr_b16 v[200:201], v193 offset:20480
	ds_read_b64_tr_b16 v[202:203], v193 offset:20992
	v_mfma_f32_32x32x16_bf16 v[114:129], v[66:69], v[76:79], v[114:129]
	v_max_f32_e32 v66, v51, v51
	v_max_f32_e32 v67, v50, v50
	v_max_f32_e32 v66, v67, v66
	v_max3_f32 v66, v66, v52, v53
	v_max3_f32 v66, v66, v54, v55
	v_max3_f32 v66, v66, v56, v57
	v_max3_f32 v82, v66, v58, v59
	v_max3_f32 v66, v82, v60, v61
	v_max3_f32 v82, v34, v35, v36
	v_max3_f32 v82, v82, v37, v38
	v_max3_f32 v82, v82, v39, v40
	v_max3_f32 v82, v82, v41, v42
	s_waitcnt lgkmcnt(2)
	v_mfma_f32_32x32x16_bf16 v[114:129], v[84:87], v[196:199], v[114:129]
	v_max3_f32 v67, v82, v43, v44
	v_max3_f32 v82, v67, v45, v46
	v_max3_f32 v83, v66, v62, v63
	s_waitcnt lgkmcnt(0)
	v_mfma_f32_32x32x16_bf16 v[98:113], v[200:203], v[196:199], v[98:113]
	v_max3_f32 v82, v82, v47, v48
	v_max3_f32 v83, v83, v64, v65
	v_max3_f32 v82, v82, v49, v83
	v_cmp_lt_f32_e32 vcc, 0x41000000, v82
	s_cbranch_vccz .LBB0_1033
; #define LAS __attribute__((address_space(3)))
; __device__ __forceinline__ void att_shift(float tm, bool first, float& mrun, float& lsum, fa::f32x16& o0, fa::f32x16& o1) {
;     if (first || __any(tm > mrun + 8.f)) {
;         tm = fmaxf(tm, __shfl_xor(tm, 32));
;         const float dl = first ? 0.f : fmaxf(tm - mrun, 0.f), alpha = __builtin_amdgcn_exp2f(-dl);
;         mrun = first ? tm : mrun + dl; lsum *= alpha;
; #pragma unroll
;         for (int r = 0; r < 16; ++r) { o0[r] *= alpha; o1[r] *= alpha; }
;     }
; }
; __device__ __forceinline__ void att_qk_exp(const LAS char* kb, const bf16x8 (&qf)[6], float nm, fa::f32x16& n0, fa::f32x16& n1, fa::f32x16& p0, fa::f32x16& p1, float& lsum, bf16x8 (&pf)[4]) {
;     const fa::f32x16 zero = {0.f, 0.f, 0.f, 0.f, 0.f, 0.f, 0.f, 0.f, 0.f, 0.f, 0.f, 0.f, 0.f, 0.f, 0.f, 0.f};
;     bf16x8 kc0 = *(const LAS bf16x8*)kb, kc1 = *(const LAS bf16x8*)(kb + 32 * fa::KP_A);
;     float ps = 0.f, ps2 = 0.f;
; #pragma unroll
;     for (int st = 0; st < 6; ++st) {
;         bf16x8 kn0 = kc0, kn1 = kc1;
;         if (st < 5) { kn0 = *(const LAS bf16x8*)(kb + 32 * (st + 1)); kn1 = *(const LAS bf16x8*)(kb + 32 * fa::KP_A + 32 * (st + 1)); }
;         n0 = __builtin_amdgcn_mfma_f32_32x32x16_bf16(kc0, qf[st], st == 0 ? zero : n0, 0, 0, 0);
;         n1 = __builtin_amdgcn_mfma_f32_32x32x16_bf16(kc1, qf[st], st == 0 ? zero : n1, 0, 0, 0);
;         constexpr int lo[7] = {0, 2, 6, 8, 10, 14, 16};
; #pragma unroll
;         for (int r = lo[st]; r < lo[st + 1]; ++r) {
;             p0[r] = __builtin_amdgcn_exp2f(vadd1(p0[r], nm)); p1[r] = __builtin_amdgcn_exp2f(vadd1(p1[r], nm));
;             ps += p0[r]; ps += p1[r]; }
;         kc0 = kn0; kc1 = kn1;
;         __builtin_amdgcn_sched_barrier(0);
;     }
;     lsum += ps + ps2;
;     pf[0] = fa::pack_p(p0, 0); pf[1] = fa::pack_p(p0, 8); pf[2] = fa::pack_p(p1, 0); pf[3] = fa::pack_p(p1, 8);
; }
; __device__ __forceinline__ void att_exp_pack(fa::f32x16& p0, fa::f32x16& p1, float nm, float& lsum, bf16x8 (&pf)[4]) {
;     float ps = 0.f, ps2 = 0.f;
; #pragma unroll
;     for (int r = 0; r < 16; ++r) { p0[r] = __builtin_amdgcn_exp2f(vadd1(p0[r], nm)); p1[r] = __builtin_amdgcn_exp2f(vadd1(p1[r], nm)); ps += p0[r]; ps += p1[r]; }
;     lsum += ps + ps2;
;     pf[0] = fa::pack_p(p0, 0); pf[1] = fa::pack_p(p0, 8); pf[2] = fa::pack_p(p1, 0); pf[3] = fa::pack_p(p1, 8);
; }
	v_and_b32_e32 v84, 64, v1
	v_xor_b32_e32 v83, 32, v1
	v_add_u32_e32 v84, 64, v84
	v_cmp_lt_i32_e32 vcc, v83, v84
	s_nop 1
	v_cndmask_b32_e32 v83, v1, v83, vcc
	v_lshlrev_b32_e32 v83, 2, v83
	ds_bpermute_b32 v83, v83, v82
	v_max_f32_e32 v82, v82, v82
	s_waitcnt lgkmcnt(0)
	v_max_f32_e32 v83, v83, v83
	v_max_f32_e32 v82, v82, v83
	v_max_f32_e32 v83, 0, v82
	v_exp_f32_e64 v82, -v83
	v_add_f32_e32 v190, v190, v83
	v_mul_f32_e32 v192, v192, v82
	v_pk_mul_f32 v[128:129], v[128:129], v[82:83] op_sel_hi:[1,0]
	v_pk_mul_f32 v[126:127], v[126:127], v[82:83] op_sel_hi:[1,0]
	v_pk_mul_f32 v[124:125], v[124:125], v[82:83] op_sel_hi:[1,0]
	v_pk_mul_f32 v[122:123], v[122:123], v[82:83] op_sel_hi:[1,0]
	v_pk_mul_f32 v[120:121], v[120:121], v[82:83] op_sel_hi:[1,0]
	v_pk_mul_f32 v[118:119], v[118:119], v[82:83] op_sel_hi:[1,0]
	v_pk_mul_f32 v[116:117], v[116:117], v[82:83] op_sel_hi:[1,0]
	v_pk_mul_f32 v[114:115], v[114:115], v[82:83] op_sel_hi:[1,0]
	v_pk_mul_f32 v[112:113], v[112:113], v[82:83] op_sel_hi:[1,0]
	v_pk_mul_f32 v[110:111], v[110:111], v[82:83] op_sel_hi:[1,0]
	v_pk_mul_f32 v[108:109], v[108:109], v[82:83] op_sel_hi:[1,0]
	v_pk_mul_f32 v[106:107], v[106:107], v[82:83] op_sel_hi:[1,0]
	v_pk_mul_f32 v[104:105], v[104:105], v[82:83] op_sel_hi:[1,0]
	v_pk_mul_f32 v[102:103], v[102:103], v[82:83] op_sel_hi:[1,0]
	v_pk_mul_f32 v[100:101], v[100:101], v[82:83] op_sel_hi:[1,0]
	v_pk_mul_f32 v[98:99], v[98:99], v[82:83] op_sel_hi:[1,0]
	v_sub_f32_e32 v34, v34, v83
	v_sub_f32_e32 v35, v35, v83
	v_sub_f32_e32 v36, v36, v83
	v_sub_f32_e32 v37, v37, v83
	v_sub_f32_e32 v38, v38, v83
	v_sub_f32_e32 v39, v39, v83
	v_sub_f32_e32 v40, v40, v83
	v_sub_f32_e32 v41, v41, v83
	v_sub_f32_e32 v42, v42, v83
	v_sub_f32_e32 v43, v43, v83
	v_sub_f32_e32 v44, v44, v83
	v_sub_f32_e32 v45, v45, v83
	v_sub_f32_e32 v46, v46, v83
	v_sub_f32_e32 v47, v47, v83
	v_sub_f32_e32 v48, v48, v83
	v_sub_f32_e32 v49, v49, v83
	v_sub_f32_e32 v50, v50, v83
	v_sub_f32_e32 v51, v51, v83
	v_sub_f32_e32 v52, v52, v83
	v_sub_f32_e32 v53, v53, v83
	v_sub_f32_e32 v54, v54, v83
	v_sub_f32_e32 v55, v55, v83
	v_sub_f32_e32 v56, v56, v83
	v_sub_f32_e32 v57, v57, v83
	v_sub_f32_e32 v58, v58, v83
	v_sub_f32_e32 v59, v59, v83
	v_sub_f32_e32 v60, v60, v83
	v_sub_f32_e32 v61, v61, v83
	v_sub_f32_e32 v62, v62, v83
	v_sub_f32_e32 v63, v63, v83
	v_sub_f32_e32 v64, v64, v83
	v_sub_f32_e32 v65, v65, v83
	v_sub_f32_e32 v226, v226, v83
	v_sub_f32_e32 v227, v227, v83
	v_sub_f32_e32 v228, v228, v83
	v_sub_f32_e32 v229, v229, v83
	v_sub_f32_e32 v230, v230, v83
	v_sub_f32_e32 v231, v231, v83
	v_sub_f32_e32 v232, v232, v83
	v_sub_f32_e32 v233, v233, v83
	v_sub_f32_e32 v234, v234, v83
	v_sub_f32_e32 v235, v235, v83
	v_sub_f32_e32 v236, v236, v83
	v_sub_f32_e32 v237, v237, v83
	v_sub_f32_e32 v238, v238, v83
	v_sub_f32_e32 v239, v239, v83
	v_sub_f32_e32 v240, v240, v83
	v_sub_f32_e32 v241, v241, v83
.LBB0_1033:
	s_mov_b64 s[8:9], -1
	s_and_b64 vcc, exec, s[10:11]
	s_barrier
	s_cbranch_vccz .LBB0_1035
	v_exp_f32_e32 v82, v34
	v_exp_f32_e32 v83, v50
	v_exp_f32_e32 v85, v35
	v_exp_f32_e32 v86, v51
	v_exp_f32_e32 v87, v36
	v_exp_f32_e32 v88, v52
	v_exp_f32_e32 v89, v37
	v_exp_f32_e32 v90, v53
	v_pk_add_f32 v[252:253], v[82:83], v[86:87]
	v_exp_f32_e32 v91, v38
	v_exp_f32_e32 v92, v54
	v_pk_add_f32 v[252:253], v[252:253], v[88:89]
	v_exp_f32_e32 v93, v39
	v_exp_f32_e32 v94, v55
	v_pk_add_f32 v[252:253], v[252:253], v[90:91]
	v_exp_f32_e32 v95, v40
	v_exp_f32_e32 v96, v56
	v_pk_add_f32 v[252:253], v[252:253], v[92:93]
	v_exp_f32_e32 v97, v41
	v_exp_f32_e32 v66, v57
	v_pk_add_f32 v[252:253], v[252:253], v[94:95]
	v_exp_f32_e32 v67, v42
	v_exp_f32_e32 v68, v58
	v_pk_add_f32 v[252:253], v[252:253], v[96:97]
	v_exp_f32_e32 v69, v43
	v_exp_f32_e32 v70, v59
	v_pk_add_f32 v[252:253], v[252:253], v[66:67]
	v_exp_f32_e32 v71, v44
	v_exp_f32_e32 v72, v60
	v_pk_add_f32 v[252:253], v[252:253], v[68:69]
	v_exp_f32_e32 v73, v45
	v_exp_f32_e32 v74, v61
	v_pk_add_f32 v[252:253], v[252:253], v[70:71]
	v_exp_f32_e32 v75, v46
	v_exp_f32_e32 v76, v62
	v_pk_add_f32 v[252:253], v[252:253], v[72:73]
	v_exp_f32_e32 v77, v47
	v_exp_f32_e32 v78, v63
	v_pk_add_f32 v[252:253], v[252:253], v[74:75]
	v_exp_f32_e32 v79, v48
	v_exp_f32_e32 v80, v64
	v_pk_add_f32 v[252:253], v[252:253], v[76:77]
	v_exp_f32_e32 v81, v49
	v_pk_add_f32 v[252:253], v[252:253], v[78:79]
	v_exp_f32_e32 v204, v65
	v_pk_add_f32 v[252:253], v[252:253], v[80:81]
	v_add_f32_e32 v84, v252, v253
	v_add_f32_e32 v84, v84, v85
	v_cvt_pk_bf16_f32 v196, v82, v85
	v_add_f32_e32 v195, v204, v84
	v_cvt_pk_bf16_f32 v197, v87, v89
	v_cvt_pk_bf16_f32 v198, v91, v93
	v_cvt_pk_bf16_f32 v199, v95, v97
	v_cvt_pk_bf16_f32 v200, v67, v69
	v_cvt_pk_bf16_f32 v201, v71, v73
	v_cvt_pk_bf16_f32 v202, v75, v77
	v_cvt_pk_bf16_f32 v203, v79, v81
	v_cvt_pk_bf16_f32 v214, v83, v86
	v_cvt_pk_bf16_f32 v215, v88, v90
	v_cvt_pk_bf16_f32 v216, v92, v94
	v_cvt_pk_bf16_f32 v217, v96, v66
	v_cvt_pk_bf16_f32 v218, v68, v70
	v_cvt_pk_bf16_f32 v219, v72, v74
	v_cvt_pk_bf16_f32 v220, v76, v78
	v_cvt_pk_bf16_f32 v221, v80, v204
	ds_read_b64_tr_b16 v[82:83], v193 offset:34816
	ds_read_b64_tr_b16 v[84:85], v193 offset:35328
	ds_read_b64_tr_b16 v[222:223], v193 offset:38912
	ds_read_b64_tr_b16 v[224:225], v193 offset:39424
	s_waitcnt lgkmcnt(2)
	v_mfma_f32_32x32x16_bf16 v[114:129], v[82:85], v[196:199], v[114:129]
	s_mov_b64 s[8:9], 0
	s_waitcnt lgkmcnt(0)
	v_mfma_f32_32x32x16_bf16 v[98:113], v[222:225], v[196:199], v[98:113]
	ds_read_b64_tr_b16 v[196:197], v193 offset:35840
	ds_read_b64_tr_b16 v[198:199], v193 offset:36352
	ds_read_b64_tr_b16 v[222:223], v193 offset:39936
	ds_read_b64_tr_b16 v[224:225], v193 offset:40448
	s_waitcnt lgkmcnt(2)
	v_mfma_f32_32x32x16_bf16 v[114:129], v[196:199], v[200:203], v[114:129]
	s_waitcnt lgkmcnt(0)
	v_mfma_f32_32x32x16_bf16 v[98:113], v[222:225], v[200:203], v[98:113]
	ds_read_b64_tr_b16 v[196:197], v193 offset:36864
	ds_read_b64_tr_b16 v[198:199], v193 offset:37376
	ds_read_b64_tr_b16 v[200:201], v193 offset:40960
	ds_read_b64_tr_b16 v[202:203], v193 offset:41472
	s_waitcnt lgkmcnt(2)
	v_mfma_f32_32x32x16_bf16 v[114:129], v[196:199], v[214:217], v[114:129]
	s_waitcnt lgkmcnt(0)
	v_mfma_f32_32x32x16_bf16 v[98:113], v[200:203], v[214:217], v[98:113]
	ds_read_b64_tr_b16 v[196:197], v193 offset:37888
	ds_read_b64_tr_b16 v[198:199], v193 offset:38400
	ds_read_b64_tr_b16 v[200:201], v193 offset:41984
	ds_read_b64_tr_b16 v[202:203], v193 offset:42496
	s_waitcnt lgkmcnt(2)
	v_mfma_f32_32x32x16_bf16 v[114:129], v[196:199], v[218:221], v[114:129]
	s_waitcnt lgkmcnt(0)
	v_mfma_f32_32x32x16_bf16 v[98:113], v[200:203], v[218:221], v[98:113]
; #define LAS __attribute__((address_space(3)))
; __device__ __forceinline__ void att_qk_exp(const LAS char* kb, const bf16x8 (&qf)[6], float nm, fa::f32x16& n0, fa::f32x16& n1, fa::f32x16& p0, fa::f32x16& p1, float& lsum, bf16x8 (&pf)[4]) {
;     const fa::f32x16 zero = {0.f, 0.f, 0.f, 0.f, 0.f, 0.f, 0.f, 0.f, 0.f, 0.f, 0.f, 0.f, 0.f, 0.f, 0.f, 0.f};
;     bf16x8 kc0 = *(const LAS bf16x8*)kb, kc1 = *(const LAS bf16x8*)(kb + 32 * fa::KP_A);
;     float ps = 0.f, ps2 = 0.f;
; #pragma unroll
;     for (int st = 0; st < 6; ++st) {
;         bf16x8 kn0 = kc0, kn1 = kc1;
;         if (st < 5) { kn0 = *(const LAS bf16x8*)(kb + 32 * (st + 1)); kn1 = *(const LAS bf16x8*)(kb + 32 * fa::KP_A + 32 * (st + 1)); }
;         n0 = __builtin_amdgcn_mfma_f32_32x32x16_bf16(kc0, qf[st], st == 0 ? zero : n0, 0, 0, 0);
;         n1 = __builtin_amdgcn_mfma_f32_32x32x16_bf16(kc1, qf[st], st == 0 ? zero : n1, 0, 0, 0);
;         constexpr int lo[7] = {0, 2, 6, 8, 10, 14, 16};
; #pragma unroll
;         for (int r = lo[st]; r < lo[st + 1]; ++r) {
;             p0[r] = __builtin_amdgcn_exp2f(vadd1(p0[r], nm)); p1[r] = __builtin_amdgcn_exp2f(vadd1(p1[r], nm));
;             ps += p0[r]; ps += p1[r]; }
;         kc0 = kn0; kc1 = kn1;
;         __builtin_amdgcn_sched_barrier(0);
;     }
;     lsum += ps + ps2;
;     pf[0] = fa::pack_p(p0, 0); pf[1] = fa::pack_p(p0, 8); pf[2] = fa::pack_p(p1, 0); pf[3] = fa::pack_p(p1, 8);
; }
; __device__ __forceinline__ void att_exp_pack(fa::f32x16& p0, fa::f32x16& p1, float nm, float& lsum, bf16x8 (&pf)[4]) {
;     float ps = 0.f, ps2 = 0.f;
; #pragma unroll
;     for (int r = 0; r < 16; ++r) { p0[r] = __builtin_amdgcn_exp2f(vadd1(p0[r], nm)); p1[r] = __builtin_amdgcn_exp2f(vadd1(p1[r], nm)); ps += p0[r]; ps += p1[r]; }
;     lsum += ps + ps2;
;     pf[0] = fa::pack_p(p0, 0); pf[1] = fa::pack_p(p0, 8); pf[2] = fa::pack_p(p1, 0); pf[3] = fa::pack_p(p1, 8);
; }
; __device__ __forceinline__ float att_pv_max(fa::f32x16& o0, fa::f32x16& o1, const LAS char* vb, const bf16x8 (&pf)[4], const fa::f32x16& n0, const fa::f32x16& n1) {
;     using namespace fa;
;     float ta = n0[0], tb = n1[0];
;     s16x4 a0 = vtr(vb), a1 = vtr(vb + 512), b0 = vtr(vb + 4096), b1 = vtr(vb + 4096 + 512);
; #pragma unroll
;     for (int ks = 0; ks < 4; ++ks) {
;         s16x4 na0 = a0, na1 = a1, nb0 = b0, nb1 = b1;
.LBB0_1035:
	s_andn2_b64 vcc, exec, s[8:9]
	s_cbranch_vccnz .LBB0_1037
	v_add_u32_e32 v66, s18, v188
	ds_read_b128 v[2:5], v66
	ds_read_b128 v[18:21], v66 offset:6656
	ds_read_b128 v[82:85], v66 offset:32
	ds_read_b128 v[86:89], v66 offset:6688
	v_exp_f32_e32 v67, v34
	v_exp_f32_e32 v68, v50
	s_waitcnt lgkmcnt(3)
	v_mfma_f32_32x32x16_bf16 v[2:17], v[2:5], v[132:135], v[226:241]
	v_exp_f32_e32 v69, v35
	v_exp_f32_e32 v70, v51
	s_waitcnt lgkmcnt(2)
	v_mfma_f32_32x32x16_bf16 v[18:33], v[18:21], v[132:135], v[226:241]
	s_waitcnt lgkmcnt(1)
	v_mfma_f32_32x32x16_bf16 v[2:17], v[82:85], v[136:139], v[2:17]
	v_exp_f32_e32 v71, v36
	ds_read_b128 v[90:93], v66 offset:64
	ds_read_b128 v[94:97], v66 offset:6720
	v_exp_f32_e32 v72, v52
	v_exp_f32_e32 v82, v37
	s_waitcnt lgkmcnt(2)
	v_mfma_f32_32x32x16_bf16 v[18:33], v[86:89], v[136:139], v[18:33]
	v_exp_f32_e32 v83, v53
	v_exp_f32_e32 v84, v38
	v_exp_f32_e32 v85, v54
	v_exp_f32_e32 v73, v39
	v_exp_f32_e32 v74, v55
	s_waitcnt lgkmcnt(1)
	v_mfma_f32_32x32x16_bf16 v[2:17], v[90:93], v[140:143], v[2:17]
	ds_read_b128 v[34:37], v66 offset:96
	ds_read_b128 v[50:53], v66 offset:6752
	v_exp_f32_e32 v86, v40
	v_exp_f32_e32 v87, v56
	s_waitcnt lgkmcnt(2)
	v_mfma_f32_32x32x16_bf16 v[18:33], v[94:97], v[140:143], v[18:33]
	v_exp_f32_e32 v88, v41
	v_exp_f32_e32 v89, v57
	s_waitcnt lgkmcnt(1)
	v_mfma_f32_32x32x16_bf16 v[2:17], v[34:37], v[144:147], v[2:17]
	ds_read_b128 v[38:41], v66 offset:128
	ds_read_b128 v[54:57], v66 offset:6784
	v_exp_f32_e32 v42, v42
	v_exp_f32_e32 v58, v58
	s_waitcnt lgkmcnt(2)
	v_mfma_f32_32x32x16_bf16 v[18:33], v[50:53], v[144:147], v[18:33]
	v_exp_f32_e32 v43, v43
	v_exp_f32_e32 v59, v59
	s_waitcnt lgkmcnt(1)
	v_mfma_f32_32x32x16_bf16 v[2:17], v[38:41], v[148:151], v[2:17]
	ds_read_b128 v[34:37], v66 offset:160
	ds_read_b128 v[50:53], v66 offset:6816
	v_exp_f32_e32 v39, v45
	s_waitcnt lgkmcnt(2)
	v_mfma_f32_32x32x16_bf16 v[18:33], v[54:57], v[148:151], v[18:33]
	v_exp_f32_e32 v61, v61
	v_exp_f32_e32 v44, v44
	v_exp_f32_e32 v40, v46
	v_exp_f32_e32 v60, v60
	v_exp_f32_e32 v62, v62
	v_exp_f32_e32 v41, v47
	v_exp_f32_e32 v63, v63
	s_waitcnt lgkmcnt(1)
	v_mfma_f32_32x32x16_bf16 v[2:17], v[34:37], v[152:155], v[2:17]
	v_exp_f32_e32 v45, v48
	v_exp_f32_e32 v54, v64
	v_mov_b32_e32 v38, v49
	v_exp_f32_e32 v49, v65
	v_pk_add_f32 v[250:251], v[68:69], v[70:71]
	v_pk_add_f32 v[250:251], v[250:251], v[82:83]
	v_pk_add_f32 v[250:251], v[250:251], v[84:85]
	v_pk_add_f32 v[250:251], v[250:251], v[72:73]
	v_pk_add_f32 v[250:251], v[250:251], v[86:87]
	v_pk_add_f32 v[250:251], v[250:251], v[88:89]
	v_pk_add_f32 v[250:251], v[250:251], v[42:43]
	v_pk_add_f32 v[250:251], v[250:251], v[58:59]
	v_pk_add_f32 v[250:251], v[250:251], v[60:61]
	s_waitcnt lgkmcnt(0)
	v_mfma_f32_32x32x16_bf16 v[18:33], v[50:53], v[152:155], v[18:33]
	v_exp_f32_e32 v46, v38
	v_pk_add_f32 v[250:251], v[250:251], v[40:41]
	v_pk_add_f32 v[250:251], v[250:251], v[62:63]
	v_pk_add_f32 v[250:251], v[250:251], v[44:45]
	v_add_f32_e32 v34, v250, v251
	v_add_f32_e32 v34, v34, v39
	v_add_f32_e32 v34, v34, v46
	v_add_f32_e32 v34, v34, v54
	v_add_f32_e32 v34, v34, v67
	v_add_f32_e32 v34, v34, v74
	v_add_f32_e32 v195, v49, v34
	v_cvt_pk_bf16_f32 v34, v67, v69
	v_cvt_pk_bf16_f32 v35, v71, v82
	v_cvt_pk_bf16_f32 v36, v84, v73
	v_cvt_pk_bf16_f32 v37, v86, v88
	v_cvt_pk_bf16_f32 v38, v42, v43
	v_cvt_pk_bf16_f32 v39, v44, v39
	v_cvt_pk_bf16_f32 v40, v40, v41
	v_cvt_pk_bf16_f32 v41, v45, v46
	v_cvt_pk_bf16_f32 v42, v68, v70
	v_cvt_pk_bf16_f32 v43, v72, v83
	v_cvt_pk_bf16_f32 v44, v85, v74
	v_cvt_pk_bf16_f32 v45, v87, v89
	v_cvt_pk_bf16_f32 v46, v58, v59
	v_cvt_pk_bf16_f32 v47, v60, v61
	v_cvt_pk_bf16_f32 v48, v62, v63
	v_cvt_pk_bf16_f32 v49, v54, v49
	ds_read_b64_tr_b16 v[50:51], v193 offset:34816
	ds_read_b64_tr_b16 v[52:53], v193 offset:35328
	ds_read_b64_tr_b16 v[54:55], v193 offset:35840
	ds_read_b64_tr_b16 v[56:57], v193 offset:36352
	s_waitcnt lgkmcnt(2)
	v_mfma_f32_32x32x16_bf16 v[114:129], v[50:53], v[34:37], v[114:129]
	ds_read_b64_tr_b16 v[50:51], v193 offset:38912
	ds_read_b64_tr_b16 v[52:53], v193 offset:39424
	ds_read_b64_tr_b16 v[58:59], v193 offset:39936
	ds_read_b64_tr_b16 v[60:61], v193 offset:40448
	s_waitcnt lgkmcnt(2)
	v_mfma_f32_32x32x16_bf16 v[98:113], v[50:53], v[34:37], v[98:113]
	ds_read_b64_tr_b16 v[34:35], v193 offset:36864
	ds_read_b64_tr_b16 v[36:37], v193 offset:37376
	ds_read_b64_tr_b16 v[50:51], v193 offset:40960
	ds_read_b64_tr_b16 v[52:53], v193 offset:41472
	v_mfma_f32_32x32x16_bf16 v[114:129], v[54:57], v[38:41], v[114:129]
	s_waitcnt lgkmcnt(4)
	v_mfma_f32_32x32x16_bf16 v[98:113], v[58:61], v[38:41], v[98:113]
	s_waitcnt lgkmcnt(2)
	v_mfma_f32_32x32x16_bf16 v[114:129], v[34:37], v[42:45], v[114:129]
	ds_read_b64_tr_b16 v[34:35], v193 offset:37888
	ds_read_b64_tr_b16 v[36:37], v193 offset:38400
	ds_read_b64_tr_b16 v[38:39], v193 offset:41984
	ds_read_b64_tr_b16 v[40:41], v193 offset:42496
	s_waitcnt lgkmcnt(4)
	v_mfma_f32_32x32x16_bf16 v[98:113], v[50:53], v[42:45], v[98:113]
	v_max_f32_e32 v42, v19, v19
	v_max_f32_e32 v43, v18, v18
	v_max_f32_e32 v42, v43, v42
	v_max3_f32 v42, v42, v20, v21
	s_waitcnt lgkmcnt(2)
	v_mfma_f32_32x32x16_bf16 v[114:129], v[34:37], v[46:49], v[114:129]
	v_max3_f32 v35, v2, v3, v4
	v_max3_f32 v42, v42, v22, v23
	v_max3_f32 v35, v35, v5, v6
	v_max3_f32 v42, v42, v24, v25
	v_max3_f32 v35, v35, v7, v8
	v_max3_f32 v34, v42, v26, v27
	v_max3_f32 v35, v35, v9, v10
	v_max3_f32 v34, v34, v28, v29
	v_max3_f32 v35, v35, v11, v12
	v_max3_f32 v35, v35, v13, v14
	v_max3_f32 v34, v34, v30, v31
	s_waitcnt lgkmcnt(0)
	v_mfma_f32_32x32x16_bf16 v[98:113], v[38:41], v[46:49], v[98:113]
	v_max3_f32 v35, v35, v15, v16
	v_max3_f32 v34, v34, v32, v33
	v_max3_f32 v191, v35, v17, v34

; #define LAS __attribute__((address_space(3)))
; __device__ __forceinline__ bf16x8 pack_p(const f32x16& p, int base) { u32x4 w; w.x = pk2(p[base], p[base + 1]); w.y = pk2(p[base + 2], p[base + 3]); w.z = pk2(p[base + 4], p[base + 5]); w.w = pk2(p[base + 6], p[base + 7]); return __builtin_bit_cast(bf16x8, w); }
; __device__ __forceinline__ float vadd1(float a, float b) { float r; asm("v_add_f32 %0, %1, %2" : "=v"(r) : "v"(a), "v"(b)); return r; }
; __device__ __forceinline__ void att_qk_exp(const LAS char* kb, const bf16x8 (&qf)[6], float nm, fa::f32x16& n0, fa::f32x16& n1, fa::f32x16& p0, fa::f32x16& p1, float& lsum, bf16x8 (&pf)[4]) {
;     const fa::f32x16 zero = {0.f, 0.f, 0.f, 0.f, 0.f, 0.f, 0.f, 0.f, 0.f, 0.f, 0.f, 0.f, 0.f, 0.f, 0.f, 0.f};
;     bf16x8 kc0 = *(const LAS bf16x8*)kb, kc1 = *(const LAS bf16x8*)(kb + 32 * fa::KP_A);
;     float ps = 0.f, ps2 = 0.f;
; #pragma unroll
;     for (int st = 0; st < 6; ++st) {
;         bf16x8 kn0 = kc0, kn1 = kc1;
;         if (st < 5) { kn0 = *(const LAS bf16x8*)(kb + 32 * (st + 1)); kn1 = *(const LAS bf16x8*)(kb + 32 * fa::KP_A + 32 * (st + 1)); }
;         n0 = __builtin_amdgcn_mfma_f32_32x32x16_bf16(kc0, qf[st], st == 0 ? zero : n0, 0, 0, 0);
;         n1 = __builtin_amdgcn_mfma_f32_32x32x16_bf16(kc1, qf[st], st == 0 ? zero : n1, 0, 0, 0);
;         constexpr int lo[7] = {0, 2, 6, 8, 10, 14, 16};
; #pragma unroll
;         for (int r = lo[st]; r < lo[st + 1]; ++r) {
;             p0[r] = __builtin_amdgcn_exp2f(vadd1(p0[r], nm)); p1[r] = __builtin_amdgcn_exp2f(vadd1(p1[r], nm));
;             ps += p0[r]; ps += p1[r]; }
;         kc0 = kn0; kc1 = kn1;
;         __builtin_amdgcn_sched_barrier(0);
;     }
;     lsum += ps + ps2;
;     pf[0] = fa::pack_p(p0, 0); pf[1] = fa::pack_p(p0, 8); pf[2] = fa::pack_p(p1, 0); pf[3] = fa::pack_p(p1, 8);
; }
.LBB0_1079:
	s_add_i32 s8, s8, 0
	v_add3_u32 v99, s8, v217, v188
	ds_read_b128 v[34:37], v99 offset:21504
	ds_read_b128 v[50:53], v99 offset:28160
	ds_read_b128 v[100:103], v99 offset:21536
	v_xor_b32_e32 v116, 0x80000000, v131
	v_add_f32 v2, v2, v116
	s_waitcnt lgkmcnt(1)
	v_mfma_f32_32x32x16_bf16 v[50:65], v[50:53], v[134:137], 0
	v_add_f32 v18, v18, v116
	ds_read_b128 v[104:107], v99 offset:28192
	v_add_f32 v3, v3, v116
	v_add_f32 v19, v19, v116
	v_exp_f32_e32 v2, v2
	v_exp_f32_e32 v18, v18
	v_exp_f32_e32 v3, v3
	v_mfma_f32_32x32x16_bf16 v[34:49], v[34:37], v[134:137], 0
	v_exp_f32_e32 v19, v19
	s_waitcnt lgkmcnt(1)
	v_mfma_f32_32x32x16_bf16 v[34:49], v[100:103], v[138:141], v[34:49]
	ds_read_b128 v[108:111], v99 offset:21568
	ds_read_b128 v[112:115], v99 offset:28224
	v_add_f32 v4, v4, v116
	v_add_f32 v20, v20, v116
	v_add_f32 v5, v5, v116
	v_add_f32 v21, v21, v116
	v_add_f32 v6, v6, v116
	v_add_f32 v22, v22, v116
	s_waitcnt lgkmcnt(2)
	v_mfma_f32_32x32x16_bf16 v[50:65], v[104:107], v[138:141], v[50:65]
	v_add_f32 v7, v7, v116
	v_add_f32 v23, v23, v116
	v_exp_f32_e32 v4, v4
	v_exp_f32_e32 v20, v20
	v_exp_f32_e32 v5, v5
	v_exp_f32_e32 v21, v21
	v_exp_f32_e32 v6, v6
	v_exp_f32_e32 v22, v22
	v_exp_f32_e32 v7, v7
	v_exp_f32_e32 v23, v23
	s_waitcnt lgkmcnt(1)
	v_mfma_f32_32x32x16_bf16 v[34:49], v[108:111], v[142:145], v[34:49]
	ds_read_b128 v[100:103], v99 offset:21600
	ds_read_b128 v[104:107], v99 offset:28256
	v_add_f32 v8, v8, v116
	v_add_f32 v24, v24, v116
	v_add_f32 v9, v9, v116
	v_add_f32 v25, v25, v116
	s_nop 0
	v_exp_f32_e32 v8, v8
	s_waitcnt lgkmcnt(2)
	v_mfma_f32_32x32x16_bf16 v[50:65], v[112:115], v[142:145], v[50:65]
	v_exp_f32_e32 v24, v24
	v_exp_f32_e32 v9, v9
	v_exp_f32_e32 v25, v25
	s_waitcnt lgkmcnt(1)
	v_mfma_f32_32x32x16_bf16 v[34:49], v[100:103], v[146:149], v[34:49]
	ds_read_b128 v[108:111], v99 offset:21632
	ds_read_b128 v[112:115], v99 offset:28288
	v_add_f32 v10, v10, v116
	v_add_f32 v26, v26, v116
	v_add_f32 v11, v11, v116
	v_add_f32 v27, v27, v116
	s_nop 0
	v_exp_f32_e32 v10, v10
	s_waitcnt lgkmcnt(2)
	v_mfma_f32_32x32x16_bf16 v[50:65], v[104:107], v[146:149], v[50:65]
	v_exp_f32_e32 v26, v26
	v_exp_f32_e32 v11, v11
	v_exp_f32_e32 v27, v27
	s_waitcnt lgkmcnt(1)
	v_mfma_f32_32x32x16_bf16 v[34:49], v[108:111], v[150:153], v[34:49]
	ds_read_b128 v[100:103], v99 offset:21664
	ds_read_b128 v[104:107], v99 offset:28320
	v_add_f32 v12, v12, v116
	v_add_f32 v28, v28, v116
	v_add_f32 v13, v13, v116
	v_add_f32 v29, v29, v116
	v_add_f32 v14, v14, v116
	v_add_f32 v30, v30, v116
	s_waitcnt lgkmcnt(2)
	v_mfma_f32_32x32x16_bf16 v[50:65], v[112:115], v[150:153], v[50:65]
	v_add_f32 v15, v15, v116
	v_add_f32 v31, v31, v116
	v_exp_f32_e32 v12, v12
	v_exp_f32_e32 v28, v28
	v_exp_f32_e32 v13, v13
	v_exp_f32_e32 v29, v29
	v_exp_f32_e32 v14, v14
	v_exp_f32_e32 v30, v30
	v_exp_f32_e32 v15, v15
	v_exp_f32_e32 v31, v31
	v_pk_add_f32 v[252:253], v[2:3], v[18:19]
	v_pk_add_f32 v[252:253], v[252:253], v[4:5]
	v_pk_add_f32 v[252:253], v[252:253], v[20:21]
	v_pk_add_f32 v[252:253], v[252:253], v[6:7]
	v_pk_add_f32 v[252:253], v[252:253], v[22:23]
	v_pk_add_f32 v[252:253], v[252:253], v[8:9]
	v_pk_add_f32 v[252:253], v[252:253], v[24:25]
	v_pk_add_f32 v[252:253], v[252:253], v[10:11]
	v_pk_add_f32 v[252:253], v[252:253], v[26:27]
	v_pk_add_f32 v[252:253], v[252:253], v[12:13]
	v_add_f32 v16, v16, v116
	v_pk_add_f32 v[252:253], v[252:253], v[28:29]
	v_exp_f32_e32 v16, v16
	v_add_f32 v32, v32, v116
	s_waitcnt lgkmcnt(1)
	v_mfma_f32_32x32x16_bf16 v[34:49], v[100:103], v[154:157], v[34:49]
	v_exp_f32_e32 v32, v32
	v_add_f32 v17, v17, v116
	v_exp_f32_e32 v17, v17
	v_add_f32 v33, v33, v116
	v_pk_add_f32 v[252:253], v[252:253], v[14:15]
	s_waitcnt lgkmcnt(0)
	v_mfma_f32_32x32x16_bf16 v[50:65], v[104:107], v[154:157], v[50:65]
	v_exp_f32_e32 v33, v33
	v_pk_add_f32 v[252:253], v[252:253], v[30:31]
	v_pk_add_f32 v[252:253], v[252:253], v[16:17]
	v_pk_add_f32 v[252:253], v[252:253], v[32:33]
	v_add_f32_e32 v99, v252, v253
	v_add_u32_e32 v221, s8, v216
	v_cvt_pk_bf16_f32 v100, v2, v3
	v_cvt_pk_bf16_f32 v101, v4, v5
	v_cvt_pk_bf16_f32 v102, v6, v7
	v_cvt_pk_bf16_f32 v103, v8, v9
	v_cvt_pk_bf16_f32 v104, v10, v11
	v_cvt_pk_bf16_f32 v105, v12, v13
	v_cvt_pk_bf16_f32 v106, v14, v15
	v_cvt_pk_bf16_f32 v107, v16, v17
	v_cvt_pk_bf16_f32 v108, v18, v19
	v_cvt_pk_bf16_f32 v109, v20, v21
	v_cvt_pk_bf16_f32 v110, v22, v23
	v_cvt_pk_bf16_f32 v111, v24, v25
	v_cvt_pk_bf16_f32 v224, v26, v27
	v_cvt_pk_bf16_f32 v225, v28, v29
	v_cvt_pk_bf16_f32 v226, v30, v31
	v_cvt_pk_bf16_f32 v227, v32, v33
	ds_read_b64_tr_b16 v[112:113], v221 offset:13312
	ds_read_b64_tr_b16 v[114:115], v221 offset:13824
	ds_read_b64_tr_b16 v[116:117], v221 offset:14336
	ds_read_b64_tr_b16 v[118:119], v221 offset:14848
	s_waitcnt lgkmcnt(2)
	v_mfma_f32_32x32x16_bf16 v[82:97], v[112:115], v[100:103], v[82:97]
	ds_read_b64_tr_b16 v[112:113], v221 offset:17408
	ds_read_b64_tr_b16 v[114:115], v221 offset:17920
	ds_read_b64_tr_b16 v[120:121], v221 offset:18432
	ds_read_b64_tr_b16 v[122:123], v221 offset:18944
	v_add_f32_e32 v99, 0, v99
	v_add_f32_e32 v220, v98, v99
	s_waitcnt lgkmcnt(2)
	v_mfma_f32_32x32x16_bf16 v[66:81], v[112:115], v[100:103], v[66:81]
	s_waitcnt lgkmcnt(0)
	v_mfma_f32_32x32x16_bf16 v[66:81], v[120:123], v[104:107], v[66:81]
	ds_read_b64_tr_b16 v[98:99], v221 offset:15360
	ds_read_b64_tr_b16 v[100:101], v221 offset:15872
	ds_read_b64_tr_b16 v[112:113], v221 offset:19456
	ds_read_b64_tr_b16 v[114:115], v221 offset:19968
	v_mfma_f32_32x32x16_bf16 v[82:97], v[116:119], v[104:107], v[82:97]
	s_waitcnt lgkmcnt(0)
; #define LAS __attribute__((address_space(3)))
; __device__ __forceinline__ s16x4 vtr(const LAS char* p) { return __builtin_bit_cast(s16x4, __builtin_amdgcn_ds_read_tr16_b64_v4i16((LAS s16x4*)p)); }
; __device__ __forceinline__ void att_shift(float tm, bool first, float& mrun, float& lsum, fa::f32x16& o0, fa::f32x16& o1) {
;     if (first || __any(tm > mrun + 8.f)) {
;         tm = fmaxf(tm, __shfl_xor(tm, 32));
;         const float dl = first ? 0.f : fmaxf(tm - mrun, 0.f), alpha = __builtin_amdgcn_exp2f(-dl);
;         mrun = first ? tm : mrun + dl; lsum *= alpha;
; #pragma unroll
;         for (int r = 0; r < 16; ++r) { o0[r] *= alpha; o1[r] *= alpha; }
;     }
; }
; __device__ __forceinline__ void att_exp_pack(fa::f32x16& p0, fa::f32x16& p1, float nm, float& lsum, bf16x8 (&pf)[4]) {
;     float ps = 0.f, ps2 = 0.f;
; #pragma unroll
;     for (int r = 0; r < 16; ++r) { p0[r] = __builtin_amdgcn_exp2f(vadd1(p0[r], nm)); p1[r] = __builtin_amdgcn_exp2f(vadd1(p1[r], nm)); ps += p0[r]; ps += p1[r]; }
;     lsum += ps + ps2;
;     pf[0] = fa::pack_p(p0, 0); pf[1] = fa::pack_p(p0, 8); pf[2] = fa::pack_p(p1, 0); pf[3] = fa::pack_p(p1, 8);
; }
; __device__ __forceinline__ float att_pv_max(fa::f32x16& o0, fa::f32x16& o1, const LAS char* vb, const bf16x8 (&pf)[4], const fa::f32x16& n0, const fa::f32x16& n1) {
;     using namespace fa;
;     float ta = n0[0], tb = n1[0];
;     s16x4 a0 = vtr(vb), a1 = vtr(vb + 512), b0 = vtr(vb + 4096), b1 = vtr(vb + 4096 + 512);
; #pragma unroll
;     for (int ks = 0; ks < 4; ++ks) {
;         s16x4 na0 = a0, na1 = a1, nb0 = b0, nb1 = b1;
;         if (ks < 3) { na0 = vtr(vb + (ks + 1) * 1024); na1 = vtr(vb + (ks + 1) * 1024 + 512); nb0 = vtr(vb + 4096 + (ks + 1) * 1024); nb1 = vtr(vb + 4096 + (ks + 1) * 1024 + 512); }
;         const bf16x8 v0 = (bf16x8){a0[0], a0[1], a0[2], a0[3], a1[0], a1[1], a1[2], a1[3]}, v1 = (bf16x8){b0[0], b0[1], b0[2], b0[3], b1[0], b1[1], b1[2], b1[3]};
;         o0 = __builtin_amdgcn_mfma_f32_32x32x16_bf16(v0, pf[ks], o0, 0, 0, 0);
;         o1 = __builtin_amdgcn_mfma_f32_32x32x16_bf16(v1, pf[ks], o1, 0, 0, 0);
; #pragma unroll
;         for (int r = 4 * ks; r < 4 * ks + 4; ++r) { ta = fmaxf(ta, n0[r]); tb = fmaxf(tb, n1[r]); }
;         a0 = na0; a1 = na1; b0 = nb0; b1 = nb1;
;         __builtin_amdgcn_sched_barrier(0);
;     }
;     return fmaxf(ta, tb);
; }
	v_mfma_f32_32x32x16_bf16 v[66:81], v[112:115], v[108:111], v[66:81]
	ds_read_b64_tr_b16 v[116:117], v221 offset:16384
	ds_read_b64_tr_b16 v[118:119], v221 offset:16896
	ds_read_b64_tr_b16 v[228:229], v221 offset:20480
	ds_read_b64_tr_b16 v[230:231], v221 offset:20992
	v_mfma_f32_32x32x16_bf16 v[82:97], v[98:101], v[108:111], v[82:97]
	v_max_f32_e32 v98, v51, v51
	v_max_f32_e32 v99, v50, v50
	v_max_f32_e32 v98, v99, v98
	v_max3_f32 v98, v98, v52, v53
	v_max3_f32 v98, v98, v54, v55
	v_max3_f32 v98, v98, v56, v57
	v_max3_f32 v114, v98, v58, v59
	s_nop 4
	v_mov_b64_e32 v[112:113], v[96:97]
	v_mov_b64_e32 v[110:111], v[94:95]
	v_mov_b64_e32 v[108:109], v[92:93]
	v_mov_b64_e32 v[106:107], v[90:91]
	v_mov_b64_e32 v[104:105], v[88:89]
	v_mov_b64_e32 v[102:103], v[86:87]
	v_mov_b64_e32 v[100:101], v[84:85]
	v_mov_b64_e32 v[98:99], v[82:83]
	v_max3_f32 v82, v114, v60, v61
	v_max3_f32 v83, v34, v35, v36
	s_waitcnt lgkmcnt(2)
	v_mfma_f32_32x32x16_bf16 v[98:113], v[116:119], v[224:227], v[98:113]
	v_mov_b64_e32 v[128:129], v[80:81]
	v_mov_b64_e32 v[126:127], v[78:79]
	v_mov_b64_e32 v[124:125], v[76:77]
	v_mov_b64_e32 v[122:123], v[74:75]
	v_mov_b64_e32 v[120:121], v[72:73]
	v_mov_b64_e32 v[118:119], v[70:71]
	v_mov_b64_e32 v[116:117], v[68:69]
	v_mov_b64_e32 v[114:115], v[66:67]
	v_max3_f32 v83, v83, v37, v38
	v_max3_f32 v83, v83, v39, v40
	s_waitcnt lgkmcnt(0)
	v_mfma_f32_32x32x16_bf16 v[114:129], v[228:231], v[224:227], v[114:129]
	v_max3_f32 v83, v83, v41, v42
	v_max3_f32 v83, v83, v43, v44
	v_max3_f32 v66, v83, v45, v46
	v_max3_f32 v67, v82, v62, v63
	v_max3_f32 v66, v66, v47, v48
	v_max3_f32 v67, v67, v64, v65
	v_max3_f32 v66, v66, v49, v67
	v_cmp_gt_f32_e32 vcc, v66, v222
	s_cbranch_vccz .LBB0_1081
	v_and_b32_e32 v68, 64, v1
	v_xor_b32_e32 v67, 32, v1
	v_add_u32_e32 v68, 64, v68
	v_cmp_lt_i32_e32 vcc, v67, v68
	s_nop 1
	v_cndmask_b32_e32 v67, v1, v67, vcc
	v_lshlrev_b32_e32 v67, 2, v67
	ds_bpermute_b32 v67, v67, v66
	v_max_f32_e32 v66, v66, v66
	s_waitcnt lgkmcnt(0)
	v_max_f32_e32 v67, v67, v67
	v_max_f32_e32 v66, v66, v67
	v_sub_f32_e32 v66, v66, v131
	v_max_f32_e32 v67, 0, v66
	v_exp_f32_e64 v66, -v67
	v_add_f32_e32 v131, v131, v67
	v_mul_f32_e32 v220, v220, v66
	v_pk_mul_f32 v[112:113], v[112:113], v[66:67] op_sel_hi:[1,0]
	v_pk_mul_f32 v[110:111], v[110:111], v[66:67] op_sel_hi:[1,0]
	v_pk_mul_f32 v[108:109], v[108:109], v[66:67] op_sel_hi:[1,0]
	v_pk_mul_f32 v[106:107], v[106:107], v[66:67] op_sel_hi:[1,0]
	v_pk_mul_f32 v[104:105], v[104:105], v[66:67] op_sel_hi:[1,0]
	v_pk_mul_f32 v[102:103], v[102:103], v[66:67] op_sel_hi:[1,0]
	v_pk_mul_f32 v[100:101], v[100:101], v[66:67] op_sel_hi:[1,0]
	v_pk_mul_f32 v[98:99], v[98:99], v[66:67] op_sel_hi:[1,0]
	v_pk_mul_f32 v[128:129], v[128:129], v[66:67] op_sel_hi:[1,0]
	v_pk_mul_f32 v[126:127], v[126:127], v[66:67] op_sel_hi:[1,0]
	v_pk_mul_f32 v[124:125], v[124:125], v[66:67] op_sel_hi:[1,0]
	v_pk_mul_f32 v[122:123], v[122:123], v[66:67] op_sel_hi:[1,0]
	v_pk_mul_f32 v[120:121], v[120:121], v[66:67] op_sel_hi:[1,0]
	v_pk_mul_f32 v[118:119], v[118:119], v[66:67] op_sel_hi:[1,0]
	v_pk_mul_f32 v[116:117], v[116:117], v[66:67] op_sel_hi:[1,0]
	v_pk_mul_f32 v[114:115], v[114:115], v[66:67] op_sel_hi:[1,0]
.LBB0_1081:
	s_mov_b64 s[8:9], -1
	s_and_b64 vcc, exec, s[12:13]
	v_xor_b32_e32 v222, 0x80000000, v131
	s_barrier
	s_cbranch_vccz .LBB0_1083
	v_add_f32 v66, v34, v222
	v_add_f32 v67, v50, v222
	v_add_f32 v69, v35, v222
	v_add_f32 v70, v51, v222
	v_add_f32 v71, v36, v222
	v_add_f32 v72, v52, v222
	s_nop 0
	v_exp_f32_e32 v66, v66
	v_exp_f32_e32 v67, v67
	v_exp_f32_e32 v69, v69
	v_exp_f32_e32 v70, v70
	v_exp_f32_e32 v71, v71
	v_exp_f32_e32 v72, v72
	v_add_f32 v73, v37, v222
	v_exp_f32_e32 v73, v73
	v_add_f32 v74, v53, v222
	v_exp_f32_e32 v74, v74
	v_add_f32 v75, v38, v222
	v_pk_add_f32 v[250:251], v[66:67], v[70:71]
	v_exp_f32_e32 v75, v75
	v_add_f32 v76, v54, v222
	v_exp_f32_e32 v76, v76
	v_add_f32 v77, v39, v222
	v_pk_add_f32 v[250:251], v[250:251], v[72:73]
	v_exp_f32_e32 v77, v77
	v_add_f32 v78, v55, v222
	v_exp_f32_e32 v78, v78
	v_add_f32 v79, v40, v222
	v_pk_add_f32 v[250:251], v[250:251], v[74:75]
	v_exp_f32_e32 v79, v79
	v_add_f32 v80, v56, v222
	v_exp_f32_e32 v80, v80
	v_add_f32 v81, v41, v222
	v_pk_add_f32 v[250:251], v[250:251], v[76:77]
	v_exp_f32_e32 v81, v81
	v_add_f32 v82, v57, v222
	v_exp_f32_e32 v82, v82
	v_add_f32 v83, v42, v222
	v_pk_add_f32 v[250:251], v[250:251], v[78:79]
	v_exp_f32_e32 v83, v83
	v_add_f32 v84, v58, v222
	v_exp_f32_e32 v84, v84
	v_add_f32 v85, v43, v222
	v_pk_add_f32 v[250:251], v[250:251], v[80:81]
	v_exp_f32_e32 v85, v85
	v_add_f32 v86, v59, v222
	v_exp_f32_e32 v86, v86
	v_add_f32 v87, v44, v222
	v_pk_add_f32 v[250:251], v[250:251], v[82:83]
	v_exp_f32_e32 v87, v87
	v_add_f32 v88, v60, v222
	v_exp_f32_e32 v88, v88
	v_add_f32 v89, v45, v222
	v_pk_add_f32 v[250:251], v[250:251], v[84:85]
	v_exp_f32_e32 v89, v89
	v_add_f32 v90, v61, v222
	v_exp_f32_e32 v90, v90
	v_add_f32 v91, v46, v222
	v_pk_add_f32 v[250:251], v[250:251], v[86:87]
	v_exp_f32_e32 v91, v91
	v_add_f32 v92, v62, v222
	v_exp_f32_e32 v92, v92
	v_add_f32 v93, v47, v222
	v_pk_add_f32 v[250:251], v[250:251], v[88:89]
	v_exp_f32_e32 v93, v93
	v_add_f32 v94, v63, v222
	v_exp_f32_e32 v94, v94
	v_add_f32 v95, v48, v222
	v_pk_add_f32 v[250:251], v[250:251], v[90:91]
	v_exp_f32_e32 v95, v95
	v_add_f32 v96, v64, v222
	v_exp_f32_e32 v96, v96
	v_add_f32 v97, v49, v222
	v_pk_add_f32 v[250:251], v[250:251], v[92:93]
	v_exp_f32_e32 v97, v97
	v_add_f32 v223, v65, v222
	v_pk_add_f32 v[250:251], v[250:251], v[94:95]
	v_exp_f32_e32 v239, v223
	v_pk_add_f32 v[250:251], v[250:251], v[96:97]
	v_add_f32_e32 v68, v250, v251
	v_add_f32_e32 v68, v68, v69
	v_cvt_pk_bf16_f32 v224, v66, v69
	v_add_f32_e32 v223, v239, v68
	v_cvt_pk_bf16_f32 v225, v71, v73
	v_cvt_pk_bf16_f32 v226, v75, v77
	v_cvt_pk_bf16_f32 v227, v79, v81
	v_cvt_pk_bf16_f32 v228, v83, v85
	v_cvt_pk_bf16_f32 v229, v87, v89
	v_cvt_pk_bf16_f32 v230, v91, v93
	v_cvt_pk_bf16_f32 v231, v95, v97
	v_cvt_pk_bf16_f32 v232, v67, v70
	v_cvt_pk_bf16_f32 v233, v72, v74
	v_cvt_pk_bf16_f32 v234, v76, v78
	v_cvt_pk_bf16_f32 v235, v80, v82
	v_cvt_pk_bf16_f32 v236, v84, v86
	v_cvt_pk_bf16_f32 v237, v88, v90
	v_cvt_pk_bf16_f32 v238, v92, v94
	v_cvt_pk_bf16_f32 v239, v96, v239
	ds_read_b64_tr_b16 v[66:67], v221 offset:34816
	ds_read_b64_tr_b16 v[68:69], v221 offset:35328
	ds_read_b64_tr_b16 v[240:241], v221 offset:38912
	ds_read_b64_tr_b16 v[242:243], v221 offset:39424
	s_waitcnt lgkmcnt(2)
; #define LAS __attribute__((address_space(3)))
; __device__ __forceinline__ s16x4 vtr(const LAS char* p) { return __builtin_bit_cast(s16x4, __builtin_amdgcn_ds_read_tr16_b64_v4i16((LAS s16x4*)p)); }
; __device__ __forceinline__ float vadd1(float a, float b) { float r; asm("v_add_f32 %0, %1, %2" : "=v"(r) : "v"(a), "v"(b)); return r; }
; __device__ __forceinline__ void pv_tile(f32x16& o0, f32x16& o1, const LAS char* vb, const bf16x8 (&pf)[4]) {
; #pragma unroll
;     for (int ks = 0; ks < 4; ++ks) {
;         const s16x4 a0 = vtr(vb + ks * 1024), a1 = vtr(vb + ks * 1024 + 512), b0 = vtr(vb + 4096 + ks * 1024), b1 = vtr(vb + 4096 + ks * 1024 + 512);
;         const bf16x8 v0 = (bf16x8){a0[0], a0[1], a0[2], a0[3], a1[0], a1[1], a1[2], a1[3]}, v1 = (bf16x8){b0[0], b0[1], b0[2], b0[3], b1[0], b1[1], b1[2], b1[3]};
;         o0 = __builtin_amdgcn_mfma_f32_32x32x16_bf16(v0, pf[ks], o0, 0, 0, 0);
;         o1 = __builtin_amdgcn_mfma_f32_32x32x16_bf16(v1, pf[ks], o1, 0, 0, 0);
;     }
; }
; __device__ __forceinline__ void att_qk_exp(const LAS char* kb, const bf16x8 (&qf)[6], float nm, fa::f32x16& n0, fa::f32x16& n1, fa::f32x16& p0, fa::f32x16& p1, float& lsum, bf16x8 (&pf)[4]) {
;     const fa::f32x16 zero = {0.f, 0.f, 0.f, 0.f, 0.f, 0.f, 0.f, 0.f, 0.f, 0.f, 0.f, 0.f, 0.f, 0.f, 0.f, 0.f};
;     bf16x8 kc0 = *(const LAS bf16x8*)kb, kc1 = *(const LAS bf16x8*)(kb + 32 * fa::KP_A);
;     float ps = 0.f, ps2 = 0.f;
; #pragma unroll
;     for (int st = 0; st < 6; ++st) {
;         bf16x8 kn0 = kc0, kn1 = kc1;
;         if (st < 5) { kn0 = *(const LAS bf16x8*)(kb + 32 * (st + 1)); kn1 = *(const LAS bf16x8*)(kb + 32 * fa::KP_A + 32 * (st + 1)); }
;         n0 = __builtin_amdgcn_mfma_f32_32x32x16_bf16(kc0, qf[st], st == 0 ? zero : n0, 0, 0, 0);
;         n1 = __builtin_amdgcn_mfma_f32_32x32x16_bf16(kc1, qf[st], st == 0 ? zero : n1, 0, 0, 0);
;         constexpr int lo[7] = {0, 2, 6, 8, 10, 14, 16};
; #pragma unroll
;         for (int r = lo[st]; r < lo[st + 1]; ++r) {
;             p0[r] = __builtin_amdgcn_exp2f(vadd1(p0[r], nm)); p1[r] = __builtin_amdgcn_exp2f(vadd1(p1[r], nm));
;             ps += p0[r]; ps += p1[r]; }
;         kc0 = kn0; kc1 = kn1;
;         __builtin_amdgcn_sched_barrier(0);
;     }
	v_mfma_f32_32x32x16_bf16 v[82:97], v[66:69], v[224:227], v[98:113]
	s_mov_b64 s[8:9], 0
	s_waitcnt lgkmcnt(0)
	v_mfma_f32_32x32x16_bf16 v[66:81], v[240:243], v[224:227], v[114:129]
	ds_read_b64_tr_b16 v[224:225], v221 offset:35840
	ds_read_b64_tr_b16 v[226:227], v221 offset:36352
	ds_read_b64_tr_b16 v[240:241], v221 offset:39936
	ds_read_b64_tr_b16 v[242:243], v221 offset:40448
	s_waitcnt lgkmcnt(2)
	v_mfma_f32_32x32x16_bf16 v[82:97], v[224:227], v[228:231], v[82:97]
	s_waitcnt lgkmcnt(0)
	v_mfma_f32_32x32x16_bf16 v[66:81], v[240:243], v[228:231], v[66:81]
	ds_read_b64_tr_b16 v[224:225], v221 offset:36864
	ds_read_b64_tr_b16 v[226:227], v221 offset:37376
	ds_read_b64_tr_b16 v[228:229], v221 offset:40960
	ds_read_b64_tr_b16 v[230:231], v221 offset:41472
	s_waitcnt lgkmcnt(2)
	v_mfma_f32_32x32x16_bf16 v[82:97], v[224:227], v[232:235], v[82:97]
	s_waitcnt lgkmcnt(0)
	v_mfma_f32_32x32x16_bf16 v[66:81], v[228:231], v[232:235], v[66:81]
	ds_read_b64_tr_b16 v[224:225], v221 offset:37888
	ds_read_b64_tr_b16 v[226:227], v221 offset:38400
	ds_read_b64_tr_b16 v[228:229], v221 offset:41984
	ds_read_b64_tr_b16 v[230:231], v221 offset:42496
	s_waitcnt lgkmcnt(2)
	v_mfma_f32_32x32x16_bf16 v[82:97], v[224:227], v[236:239], v[82:97]
	s_waitcnt lgkmcnt(0)
	v_mfma_f32_32x32x16_bf16 v[66:81], v[228:231], v[236:239], v[66:81]
.LBB0_1083:
	s_andn2_b64 vcc, exec, s[8:9]
	s_cbranch_vccnz .LBB0_1085
	s_nop 7
	v_add_u32_e32 v82, s20, v218
	ds_read_b128 v[2:5], v82
	ds_read_b128 v[18:21], v82 offset:6656
	ds_read_b128 v[66:69], v82 offset:32
	v_add_f32 v22, v34, v222
	v_add_f32 v23, v50, v222
	v_add_f32 v24, v35, v222
	ds_read_b128 v[70:73], v82 offset:6688
	v_exp_f32_e32 v83, v22
	v_add_f32 v22, v51, v222
	v_exp_f32_e32 v84, v23
	s_waitcnt lgkmcnt(3)
	v_mfma_f32_32x32x16_bf16 v[2:17], v[2:5], v[134:137], 0
	v_exp_f32_e32 v85, v24
	v_exp_f32_e32 v86, v22
	s_waitcnt lgkmcnt(2)
	v_mfma_f32_32x32x16_bf16 v[18:33], v[18:21], v[134:137], 0
	v_add_f32 v34, v36, v222
	s_waitcnt lgkmcnt(1)
	v_mfma_f32_32x32x16_bf16 v[2:17], v[66:69], v[138:141], v[2:17]
	v_exp_f32_e32 v87, v34
	v_add_f32 v34, v52, v222
	ds_read_b128 v[74:77], v82 offset:64
	ds_read_b128 v[78:81], v82 offset:6720
	v_exp_f32_e32 v88, v34
	v_add_f32 v34, v37, v222
	s_nop 0
	v_exp_f32_e32 v66, v34
	v_add_f32 v34, v53, v222
	s_waitcnt lgkmcnt(2)
	v_mfma_f32_32x32x16_bf16 v[18:33], v[70:73], v[138:141], v[18:33]
	v_exp_f32_e32 v67, v34
	v_add_f32 v34, v38, v222
	s_nop 0
	v_exp_f32_e32 v68, v34
	v_add_f32 v34, v54, v222
	s_nop 0
	v_exp_f32_e32 v69, v34
	v_add_f32 v34, v39, v222
	s_nop 0
	v_exp_f32_e32 v89, v34
	v_add_f32 v34, v55, v222
	s_nop 0
	v_exp_f32_e32 v90, v34
	s_waitcnt lgkmcnt(1)
	v_mfma_f32_32x32x16_bf16 v[2:17], v[74:77], v[142:145], v[2:17]
	v_add_f32 v38, v40, v222
	ds_read_b128 v[34:37], v82 offset:96
	ds_read_b128 v[50:53], v82 offset:6752
	v_exp_f32_e32 v70, v38
	v_add_f32 v38, v56, v222
	s_nop 0
	v_exp_f32_e32 v71, v38
	v_add_f32 v38, v41, v222
	s_waitcnt lgkmcnt(2)
	v_mfma_f32_32x32x16_bf16 v[18:33], v[78:81], v[142:145], v[18:33]
	v_exp_f32_e32 v72, v38
	v_add_f32 v38, v57, v222
	s_nop 0
	v_exp_f32_e32 v73, v38
	s_waitcnt lgkmcnt(1)
	v_mfma_f32_32x32x16_bf16 v[2:17], v[34:37], v[146:149], v[2:17]
	ds_read_b128 v[38:41], v82 offset:128
	ds_read_b128 v[54:57], v82 offset:6784
	v_add_f32 v34, v42, v222
	s_nop 0
	v_exp_f32_e32 v42, v34
	v_add_f32 v34, v58, v222
	s_nop 0
	v_exp_f32_e32 v58, v34
	s_waitcnt lgkmcnt(2)
	v_mfma_f32_32x32x16_bf16 v[18:33], v[50:53], v[146:149], v[18:33]
	v_add_f32 v34, v43, v222
	s_nop 0
	v_exp_f32_e32 v43, v34
	v_add_f32 v34, v59, v222
	s_nop 0
	v_exp_f32_e32 v59, v34
	s_waitcnt lgkmcnt(1)
	v_mfma_f32_32x32x16_bf16 v[2:17], v[38:41], v[150:153], v[2:17]
	ds_read_b128 v[34:37], v82 offset:160
	ds_read_b128 v[50:53], v82 offset:6816
	v_add_f32 v38, v45, v222
	v_add_f32 v44, v44, v222
	v_add_f32 v60, v60, v222
	s_nop 0
	v_exp_f32_e32 v39, v38
	v_add_f32 v38, v61, v222
	s_waitcnt lgkmcnt(2)
	v_mfma_f32_32x32x16_bf16 v[18:33], v[54:57], v[150:153], v[18:33]
	v_exp_f32_e32 v61, v38
	v_add_f32 v38, v46, v222
	v_exp_f32_e32 v44, v44
	v_exp_f32_e32 v40, v38
	v_add_f32 v38, v62, v222
	v_exp_f32_e32 v60, v60
	v_exp_f32_e32 v62, v38
	v_add_f32 v38, v47, v222
	s_nop 0
	v_exp_f32_e32 v41, v38
	v_add_f32 v38, v63, v222
	s_nop 0
	v_exp_f32_e32 v63, v38
	v_add_f32 v38, v48, v222
	s_waitcnt lgkmcnt(1)
; #define LAS __attribute__((address_space(3)))
; __device__ __forceinline__ void att_qk_exp(const LAS char* kb, const bf16x8 (&qf)[6], float nm, fa::f32x16& n0, fa::f32x16& n1, fa::f32x16& p0, fa::f32x16& p1, float& lsum, bf16x8 (&pf)[4]) {
;     ...
; #pragma unroll
;         for (int r = lo[st]; r < lo[st + 1]; ++r) {
;             p0[r] = __builtin_amdgcn_exp2f(vadd1(p0[r], nm)); p1[r] = __builtin_amdgcn_exp2f(vadd1(p1[r], nm));
;             ps += p0[r]; ps += p1[r]; }
;         kc0 = kn0; kc1 = kn1;
;         __builtin_amdgcn_sched_barrier(0);
;     }
;     lsum += ps + ps2;
;     pf[0] = fa::pack_p(p0, 0); pf[1] = fa::pack_p(p0, 8); pf[2] = fa::pack_p(p1, 0); pf[3] = fa::pack_p(p1, 8);
; }
; __device__ __forceinline__ void att_exp_pack(fa::f32x16& p0, fa::f32x16& p1, float nm, float& lsum, bf16x8 (&pf)[4]) {
;     float ps = 0.f, ps2 = 0.f;
; #pragma unroll
;     for (int r = 0; r < 16; ++r) { p0[r] = __builtin_amdgcn_exp2f(vadd1(p0[r], nm)); p1[r] = __builtin_amdgcn_exp2f(vadd1(p1[r], nm)); ps += p0[r]; ps += p1[r]; }
;     lsum += ps + ps2;
;     pf[0] = fa::pack_p(p0, 0); pf[1] = fa::pack_p(p0, 8); pf[2] = fa::pack_p(p1, 0); pf[3] = fa::pack_p(p1, 8);
; }
; __device__ __forceinline__ float att_pv_max(fa::f32x16& o0, fa::f32x16& o1, const LAS char* vb, const bf16x8 (&pf)[4], const fa::f32x16& n0, const fa::f32x16& n1) {
;     using namespace fa;
;     float ta = n0[0], tb = n1[0];
;     s16x4 a0 = vtr(vb), a1 = vtr(vb + 512), b0 = vtr(vb + 4096), b1 = vtr(vb + 4096 + 512);
; #pragma unroll
;     for (int ks = 0; ks < 4; ++ks) {
;         s16x4 na0 = a0, na1 = a1, nb0 = b0, nb1 = b1;
;         if (ks < 3) { na0 = vtr(vb + (ks + 1) * 1024); na1 = vtr(vb + (ks + 1) * 1024 + 512); nb0 = vtr(vb + 4096 + (ks + 1) * 1024); nb1 = vtr(vb + 4096 + (ks + 1) * 1024 + 512); }
;         const bf16x8 v0 = (bf16x8){a0[0], a0[1], a0[2], a0[3], a1[0], a1[1], a1[2], a1[3]}, v1 = (bf16x8){b0[0], b0[1], b0[2], b0[3], b1[0], b1[1], b1[2], b1[3]};
;         o0 = __builtin_amdgcn_mfma_f32_32x32x16_bf16(v0, pf[ks], o0, 0, 0, 0);
;         o1 = __builtin_amdgcn_mfma_f32_32x32x16_bf16(v1, pf[ks], o1, 0, 0, 0);
; #pragma unroll
;         for (int r = 4 * ks; r < 4 * ks + 4; ++r) { ta = fmaxf(ta, n0[r]); tb = fmaxf(tb, n1[r]); }
;         a0 = na0; a1 = na1; b0 = nb0; b1 = nb1;
;         __builtin_amdgcn_sched_barrier(0);
;     }
;     return fmaxf(ta, tb);
; }
	v_mfma_f32_32x32x16_bf16 v[2:17], v[34:37], v[154:157], v[2:17]
	v_exp_f32_e32 v45, v38
	v_add_f32 v38, v64, v222
	v_add_f32 v34, v65, v222
	s_nop 0
	v_exp_f32_e32 v54, v38
	v_add_f32 v38, v49, v222
	v_exp_f32_e32 v49, v34
	v_pk_add_f32 v[252:253], v[84:85], v[86:87]
	v_pk_add_f32 v[252:253], v[252:253], v[66:67]
	v_pk_add_f32 v[252:253], v[252:253], v[68:69]
	v_pk_add_f32 v[252:253], v[252:253], v[88:89]
	v_pk_add_f32 v[252:253], v[252:253], v[70:71]
	v_pk_add_f32 v[252:253], v[252:253], v[72:73]
	v_pk_add_f32 v[252:253], v[252:253], v[42:43]
	v_pk_add_f32 v[252:253], v[252:253], v[58:59]
	v_pk_add_f32 v[252:253], v[252:253], v[60:61]
	s_waitcnt lgkmcnt(0)
	v_mfma_f32_32x32x16_bf16 v[18:33], v[50:53], v[154:157], v[18:33]
	v_exp_f32_e32 v46, v38
	v_pk_add_f32 v[252:253], v[252:253], v[40:41]
	v_pk_add_f32 v[252:253], v[252:253], v[62:63]
	v_pk_add_f32 v[252:253], v[252:253], v[44:45]
	v_add_f32_e32 v34, v252, v253
	v_add_f32_e32 v34, v34, v39
	v_add_f32_e32 v34, v34, v46
	v_add_f32_e32 v34, v34, v54
	v_add_f32_e32 v34, v34, v83
	v_add_f32_e32 v34, v34, v90
	v_add_f32_e32 v223, v49, v34
	v_cvt_pk_bf16_f32 v34, v83, v85
	v_cvt_pk_bf16_f32 v35, v87, v66
	v_cvt_pk_bf16_f32 v36, v68, v89
	v_cvt_pk_bf16_f32 v37, v70, v72
	v_cvt_pk_bf16_f32 v38, v42, v43
	v_cvt_pk_bf16_f32 v39, v44, v39
	v_cvt_pk_bf16_f32 v40, v40, v41
	v_cvt_pk_bf16_f32 v41, v45, v46
	v_cvt_pk_bf16_f32 v42, v84, v86
	v_cvt_pk_bf16_f32 v43, v88, v67
	v_cvt_pk_bf16_f32 v44, v69, v90
	v_cvt_pk_bf16_f32 v45, v71, v73
	v_cvt_pk_bf16_f32 v46, v58, v59
	v_cvt_pk_bf16_f32 v47, v60, v61
	v_cvt_pk_bf16_f32 v48, v62, v63
	v_cvt_pk_bf16_f32 v49, v54, v49
	ds_read_b64_tr_b16 v[50:51], v221 offset:34816
	ds_read_b64_tr_b16 v[52:53], v221 offset:35328
	ds_read_b64_tr_b16 v[54:55], v221 offset:35840
	ds_read_b64_tr_b16 v[56:57], v221 offset:36352
	s_waitcnt lgkmcnt(2)
	v_mfma_f32_32x32x16_bf16 v[98:113], v[50:53], v[34:37], v[98:113]
	ds_read_b64_tr_b16 v[50:51], v221 offset:38912
	ds_read_b64_tr_b16 v[52:53], v221 offset:39424
	ds_read_b64_tr_b16 v[58:59], v221 offset:39936
	ds_read_b64_tr_b16 v[60:61], v221 offset:40448
	s_waitcnt lgkmcnt(2)
	v_mfma_f32_32x32x16_bf16 v[114:129], v[50:53], v[34:37], v[114:129]
	ds_read_b64_tr_b16 v[34:35], v221 offset:36864
	ds_read_b64_tr_b16 v[36:37], v221 offset:37376
	ds_read_b64_tr_b16 v[50:51], v221 offset:40960
	ds_read_b64_tr_b16 v[52:53], v221 offset:41472
	v_mfma_f32_32x32x16_bf16 v[98:113], v[54:57], v[38:41], v[98:113]
	s_waitcnt lgkmcnt(4)
	v_mfma_f32_32x32x16_bf16 v[114:129], v[58:61], v[38:41], v[114:129]
	s_waitcnt lgkmcnt(2)
	v_mfma_f32_32x32x16_bf16 v[98:113], v[34:37], v[42:45], v[98:113]
	ds_read_b64_tr_b16 v[34:35], v221 offset:37888
	ds_read_b64_tr_b16 v[36:37], v221 offset:38400
	ds_read_b64_tr_b16 v[38:39], v221 offset:41984
	ds_read_b64_tr_b16 v[40:41], v221 offset:42496
	s_waitcnt lgkmcnt(4)
	v_mfma_f32_32x32x16_bf16 v[114:129], v[50:53], v[42:45], v[114:129]
	v_max_f32_e32 v42, v19, v19
	v_max_f32_e32 v43, v18, v18
	v_max_f32_e32 v42, v43, v42
	v_max3_f32 v42, v42, v20, v21
	s_waitcnt lgkmcnt(2)
	v_mfma_f32_32x32x16_bf16 v[98:113], v[34:37], v[46:49], v[98:113]
	v_max3_f32 v35, v2, v3, v4
	v_max3_f32 v42, v42, v22, v23
	v_max3_f32 v35, v35, v5, v6
	v_max3_f32 v42, v42, v24, v25
	v_max3_f32 v35, v35, v7, v8
	v_max3_f32 v34, v42, v26, v27
	v_max3_f32 v35, v35, v9, v10
	v_max3_f32 v34, v34, v28, v29
	v_max3_f32 v35, v35, v11, v12
	v_max3_f32 v35, v35, v13, v14
	v_max3_f32 v34, v34, v30, v31
	s_waitcnt lgkmcnt(0)
	v_mfma_f32_32x32x16_bf16 v[114:129], v[38:41], v[46:49], v[114:129]
	v_max3_f32 v35, v35, v15, v16
	v_max3_f32 v34, v34, v32, v33
	v_mov_b64_e32 v[82:83], v[98:99]
	s_nop 8
	v_mov_b64_e32 v[66:67], v[114:115]
	v_max3_f32 v201, v35, v17, v34
	v_mov_b64_e32 v[84:85], v[100:101]
	v_mov_b64_e32 v[86:87], v[102:103]
	v_mov_b64_e32 v[88:89], v[104:105]
	v_mov_b64_e32 v[90:91], v[106:107]
	v_mov_b64_e32 v[92:93], v[108:109]
	v_mov_b64_e32 v[94:95], v[110:111]
	v_mov_b64_e32 v[96:97], v[112:113]
	v_mov_b64_e32 v[68:69], v[116:117]
	v_mov_b64_e32 v[70:71], v[118:119]
	v_mov_b64_e32 v[72:73], v[120:121]
	v_mov_b64_e32 v[74:75], v[122:123]
	v_mov_b64_e32 v[76:77], v[124:125]
	v_mov_b64_e32 v[78:79], v[126:127]
	v_mov_b64_e32 v[80:81], v[128:129]

; #define LAS __attribute__((address_space(3)))
; __device__ __forceinline__ void att_qk_exp(const LAS char* kb, const bf16x8 (&qf)[6], float nm, fa::f32x16& n0, fa::f32x16& n1, fa::f32x16& p0, fa::f32x16& p1, float& lsum, bf16x8 (&pf)[4]) {
;     const fa::f32x16 zero = {0.f, 0.f, 0.f, 0.f, 0.f, 0.f, 0.f, 0.f, 0.f, 0.f, 0.f, 0.f, 0.f, 0.f, 0.f, 0.f};
;     bf16x8 kc0 = *(const LAS bf16x8*)kb, kc1 = *(const LAS bf16x8*)(kb + 32 * fa::KP_A);
;     float ps = 0.f, ps2 = 0.f;
; #pragma unroll
;     for (int st = 0; st < 6; ++st) {
;         bf16x8 kn0 = kc0, kn1 = kc1;
;         if (st < 5) { kn0 = *(const LAS bf16x8*)(kb + 32 * (st + 1)); kn1 = *(const LAS bf16x8*)(kb + 32 * fa::KP_A + 32 * (st + 1)); }
;         n0 = __builtin_amdgcn_mfma_f32_32x32x16_bf16(kc0, qf[st], st == 0 ? zero : n0, 0, 0, 0);
;         n1 = __builtin_amdgcn_mfma_f32_32x32x16_bf16(kc1, qf[st], st == 0 ? zero : n1, 0, 0, 0);
;         constexpr int lo[7] = {0, 2, 6, 8, 10, 14, 16};
; #pragma unroll
;         for (int r = lo[st]; r < lo[st + 1]; ++r) {
;             p0[r] = __builtin_amdgcn_exp2f(vadd1(p0[r], nm)); p1[r] = __builtin_amdgcn_exp2f(vadd1(p1[r], nm));
;             ps += p0[r]; ps += p1[r]; }
;         kc0 = kn0; kc1 = kn1;
;         __builtin_amdgcn_sched_barrier(0);
;     }
;     lsum += ps + ps2;
;     pf[0] = fa::pack_p(p0, 0); pf[1] = fa::pack_p(p0, 8); pf[2] = fa::pack_p(p1, 0); pf[3] = fa::pack_p(p1, 8);
; }
; __device__ __forceinline__ void att_exp_pack(fa::f32x16& p0, fa::f32x16& p1, float nm, float& lsum, bf16x8 (&pf)[4]) {
;     float ps = 0.f, ps2 = 0.f;
; #pragma unroll
;     for (int r = 0; r < 16; ++r) { p0[r] = __builtin_amdgcn_exp2f(vadd1(p0[r], nm)); p1[r] = __builtin_amdgcn_exp2f(vadd1(p1[r], nm)); ps += p0[r]; ps += p1[r]; }
;     lsum += ps + ps2;
;     pf[0] = fa::pack_p(p0, 0); pf[1] = fa::pack_p(p0, 8); pf[2] = fa::pack_p(p1, 0); pf[3] = fa::pack_p(p1, 8);
; }
; __device__ __forceinline__ float att_pv_max(fa::f32x16& o0, fa::f32x16& o1, const LAS char* vb, const bf16x8 (&pf)[4], const fa::f32x16& n0, const fa::f32x16& n1) {
;     using namespace fa;
;     float ta = n0[0], tb = n1[0];
;     s16x4 a0 = vtr(vb), a1 = vtr(vb + 512), b0 = vtr(vb + 4096), b1 = vtr(vb + 4096 + 512);
; #pragma unroll
;     for (int ks = 0; ks < 4; ++ks) {
;         s16x4 na0 = a0, na1 = a1, nb0 = b0, nb1 = b1;
.LBB0_2991:
	s_add_i32 s8, s8, 0
	v_add3_u32 v99, s8, v217, v188
	ds_read_b128 v[34:37], v99 offset:21504
	ds_read_b128 v[50:53], v99 offset:28160
	ds_read_b128 v[100:103], v99 offset:21536
	s_waitcnt lgkmcnt(1)
	v_mfma_f32_32x32x16_bf16 v[50:65], v[50:53], v[134:137], v[232:247]
	ds_read_b128 v[104:107], v99 offset:28192
	v_exp_f32_e32 v2, v2
	v_exp_f32_e32 v18, v18
	v_exp_f32_e32 v3, v3
	v_mfma_f32_32x32x16_bf16 v[34:49], v[34:37], v[134:137], v[232:247]
	v_exp_f32_e32 v19, v19
	s_waitcnt lgkmcnt(1)
	v_mfma_f32_32x32x16_bf16 v[34:49], v[100:103], v[138:141], v[34:49]
	ds_read_b128 v[108:111], v99 offset:21568
	ds_read_b128 v[112:115], v99 offset:28224
	s_waitcnt lgkmcnt(2)
	v_mfma_f32_32x32x16_bf16 v[50:65], v[104:107], v[138:141], v[50:65]
	v_exp_f32_e32 v4, v4
	v_exp_f32_e32 v20, v20
	v_exp_f32_e32 v5, v5
	v_exp_f32_e32 v21, v21
	v_exp_f32_e32 v6, v6
	v_exp_f32_e32 v22, v22
	v_exp_f32_e32 v7, v7
	v_exp_f32_e32 v23, v23
	s_waitcnt lgkmcnt(1)
	v_mfma_f32_32x32x16_bf16 v[34:49], v[108:111], v[142:145], v[34:49]
	ds_read_b128 v[100:103], v99 offset:21600
	ds_read_b128 v[104:107], v99 offset:28256
	v_exp_f32_e32 v8, v8
	s_waitcnt lgkmcnt(2)
	v_mfma_f32_32x32x16_bf16 v[50:65], v[112:115], v[142:145], v[50:65]
	v_exp_f32_e32 v24, v24
	v_exp_f32_e32 v9, v9
	v_exp_f32_e32 v25, v25
	s_waitcnt lgkmcnt(1)
	v_mfma_f32_32x32x16_bf16 v[34:49], v[100:103], v[146:149], v[34:49]
	ds_read_b128 v[108:111], v99 offset:21632
	ds_read_b128 v[112:115], v99 offset:28288
	v_exp_f32_e32 v10, v10
	s_waitcnt lgkmcnt(2)
	v_mfma_f32_32x32x16_bf16 v[50:65], v[104:107], v[146:149], v[50:65]
	v_exp_f32_e32 v26, v26
	v_exp_f32_e32 v11, v11
	v_exp_f32_e32 v27, v27
	s_waitcnt lgkmcnt(1)
	v_mfma_f32_32x32x16_bf16 v[34:49], v[108:111], v[150:153], v[34:49]
	ds_read_b128 v[100:103], v99 offset:21664
	ds_read_b128 v[104:107], v99 offset:28320
	s_waitcnt lgkmcnt(2)
	v_mfma_f32_32x32x16_bf16 v[50:65], v[112:115], v[150:153], v[50:65]
	v_exp_f32_e32 v12, v12
	v_exp_f32_e32 v28, v28
	v_exp_f32_e32 v13, v13
	v_exp_f32_e32 v29, v29
	v_exp_f32_e32 v14, v14
	v_exp_f32_e32 v30, v30
	v_exp_f32_e32 v15, v15
	v_exp_f32_e32 v31, v31
	v_pk_add_f32 v[250:251], v[2:3], v[18:19]
	v_pk_add_f32 v[250:251], v[250:251], v[4:5]
	v_pk_add_f32 v[250:251], v[250:251], v[20:21]
	v_pk_add_f32 v[250:251], v[250:251], v[6:7]
	v_pk_add_f32 v[250:251], v[250:251], v[22:23]
	v_pk_add_f32 v[250:251], v[250:251], v[8:9]
	v_pk_add_f32 v[250:251], v[250:251], v[24:25]
	v_pk_add_f32 v[250:251], v[250:251], v[10:11]
	v_pk_add_f32 v[250:251], v[250:251], v[26:27]
	v_pk_add_f32 v[250:251], v[250:251], v[12:13]
	v_pk_add_f32 v[250:251], v[250:251], v[28:29]
	v_exp_f32_e32 v16, v16
	s_waitcnt lgkmcnt(1)
	v_mfma_f32_32x32x16_bf16 v[34:49], v[100:103], v[154:157], v[34:49]
	v_exp_f32_e32 v32, v32
	v_exp_f32_e32 v17, v17
	v_pk_add_f32 v[250:251], v[250:251], v[14:15]
	s_waitcnt lgkmcnt(0)
	v_mfma_f32_32x32x16_bf16 v[50:65], v[104:107], v[154:157], v[50:65]
	v_exp_f32_e32 v33, v33
	v_pk_add_f32 v[250:251], v[250:251], v[30:31]
	v_pk_add_f32 v[250:251], v[250:251], v[16:17]
	v_pk_add_f32 v[250:251], v[250:251], v[32:33]
	v_add_f32_e32 v99, v250, v251
	v_add_u32_e32 v221, s8, v216
	v_cvt_pk_bf16_f32 v100, v2, v3
	v_cvt_pk_bf16_f32 v101, v4, v5
	v_cvt_pk_bf16_f32 v102, v6, v7
	v_cvt_pk_bf16_f32 v103, v8, v9
	v_cvt_pk_bf16_f32 v104, v10, v11
	v_cvt_pk_bf16_f32 v105, v12, v13
	v_cvt_pk_bf16_f32 v106, v14, v15
	v_cvt_pk_bf16_f32 v107, v16, v17
	v_cvt_pk_bf16_f32 v108, v18, v19
	v_cvt_pk_bf16_f32 v109, v20, v21
	v_cvt_pk_bf16_f32 v110, v22, v23
	v_cvt_pk_bf16_f32 v111, v24, v25
	v_cvt_pk_bf16_f32 v224, v26, v27
	v_cvt_pk_bf16_f32 v225, v28, v29
	v_cvt_pk_bf16_f32 v226, v30, v31
	v_cvt_pk_bf16_f32 v227, v32, v33
	ds_read_b64_tr_b16 v[112:113], v221 offset:13312
	ds_read_b64_tr_b16 v[114:115], v221 offset:13824
	ds_read_b64_tr_b16 v[116:117], v221 offset:14336
	ds_read_b64_tr_b16 v[118:119], v221 offset:14848
	s_waitcnt lgkmcnt(2)
	v_mfma_f32_32x32x16_bf16 v[82:97], v[112:115], v[100:103], v[82:97]
	ds_read_b64_tr_b16 v[112:113], v221 offset:17408
	ds_read_b64_tr_b16 v[114:115], v221 offset:17920
	ds_read_b64_tr_b16 v[120:121], v221 offset:18432
	ds_read_b64_tr_b16 v[122:123], v221 offset:18944
	v_add_f32_e32 v220, v98, v99
	s_waitcnt lgkmcnt(2)
	v_mfma_f32_32x32x16_bf16 v[66:81], v[112:115], v[100:103], v[66:81]
	s_waitcnt lgkmcnt(0)
	v_mfma_f32_32x32x16_bf16 v[66:81], v[120:123], v[104:107], v[66:81]
	ds_read_b64_tr_b16 v[98:99], v221 offset:15360
	ds_read_b64_tr_b16 v[100:101], v221 offset:15872
	ds_read_b64_tr_b16 v[112:113], v221 offset:19456
	ds_read_b64_tr_b16 v[114:115], v221 offset:19968
	v_mfma_f32_32x32x16_bf16 v[82:97], v[116:119], v[104:107], v[82:97]
	s_waitcnt lgkmcnt(0)
	v_mfma_f32_32x32x16_bf16 v[66:81], v[112:115], v[108:111], v[66:81]
	ds_read_b64_tr_b16 v[116:117], v221 offset:16384
	ds_read_b64_tr_b16 v[118:119], v221 offset:16896
	ds_read_b64_tr_b16 v[228:229], v221 offset:20480
	ds_read_b64_tr_b16 v[230:231], v221 offset:20992
	v_mfma_f32_32x32x16_bf16 v[82:97], v[98:101], v[108:111], v[82:97]
	v_max_f32_e32 v98, v51, v51
	v_max_f32_e32 v99, v50, v50
	v_max_f32_e32 v98, v99, v98
	v_max3_f32 v98, v98, v52, v53
	v_max3_f32 v98, v98, v54, v55
	v_max3_f32 v98, v98, v56, v57
	v_max3_f32 v114, v98, v58, v59
	v_max3_f32 v98, v114, v60, v61
	v_max3_f32 v99, v34, v35, v36
	s_waitcnt lgkmcnt(2)
	v_mfma_f32_32x32x16_bf16 v[82:97], v[116:119], v[224:227], v[82:97]
	v_max3_f32 v99, v99, v37, v38
	v_max3_f32 v99, v99, v39, v40
	s_waitcnt lgkmcnt(0)
	v_mfma_f32_32x32x16_bf16 v[66:81], v[228:231], v[224:227], v[66:81]
	v_max3_f32 v99, v99, v41, v42
	v_max3_f32 v99, v99, v43, v44
	v_max3_f32 v114, v99, v45, v46
	v_max3_f32 v115, v98, v62, v63
	v_max3_f32 v114, v114, v47, v48
	v_max3_f32 v115, v115, v64, v65
	v_max3_f32 v114, v114, v49, v115
	v_cmp_lt_f32_e32 vcc, 0x41000000, v114
	s_cbranch_vccz .LBB0_2993
; #define LAS __attribute__((address_space(3)))
; __device__ __forceinline__ void att_shift(float tm, bool first, float& mrun, float& lsum, fa::f32x16& o0, fa::f32x16& o1) {
;     if (first || __any(tm > mrun + 8.f)) {
;         tm = fmaxf(tm, __shfl_xor(tm, 32));
;         const float dl = first ? 0.f : fmaxf(tm - mrun, 0.f), alpha = __builtin_amdgcn_exp2f(-dl);
;         mrun = first ? tm : mrun + dl; lsum *= alpha;
; #pragma unroll
;         for (int r = 0; r < 16; ++r) { o0[r] *= alpha; o1[r] *= alpha; }
;     }
; }
; __device__ __forceinline__ void att_qk_exp(const LAS char* kb, const bf16x8 (&qf)[6], float nm, fa::f32x16& n0, fa::f32x16& n1, fa::f32x16& p0, fa::f32x16& p1, float& lsum, bf16x8 (&pf)[4]) {
;     const fa::f32x16 zero = {0.f, 0.f, 0.f, 0.f, 0.f, 0.f, 0.f, 0.f, 0.f, 0.f, 0.f, 0.f, 0.f, 0.f, 0.f, 0.f};
;     bf16x8 kc0 = *(const LAS bf16x8*)kb, kc1 = *(const LAS bf16x8*)(kb + 32 * fa::KP_A);
;     float ps = 0.f, ps2 = 0.f;
; #pragma unroll
;     for (int st = 0; st < 6; ++st) {
;         bf16x8 kn0 = kc0, kn1 = kc1;
;         if (st < 5) { kn0 = *(const LAS bf16x8*)(kb + 32 * (st + 1)); kn1 = *(const LAS bf16x8*)(kb + 32 * fa::KP_A + 32 * (st + 1)); }
;         n0 = __builtin_amdgcn_mfma_f32_32x32x16_bf16(kc0, qf[st], st == 0 ? zero : n0, 0, 0, 0);
;         n1 = __builtin_amdgcn_mfma_f32_32x32x16_bf16(kc1, qf[st], st == 0 ? zero : n1, 0, 0, 0);
;         constexpr int lo[7] = {0, 2, 6, 8, 10, 14, 16};
; #pragma unroll
;         for (int r = lo[st]; r < lo[st + 1]; ++r) {
;             p0[r] = __builtin_amdgcn_exp2f(vadd1(p0[r], nm)); p1[r] = __builtin_amdgcn_exp2f(vadd1(p1[r], nm));
;             ps += p0[r]; ps += p1[r]; }
;         kc0 = kn0; kc1 = kn1;
;         __builtin_amdgcn_sched_barrier(0);
;     }
;     lsum += ps + ps2;
;     pf[0] = fa::pack_p(p0, 0); pf[1] = fa::pack_p(p0, 8); pf[2] = fa::pack_p(p1, 0); pf[3] = fa::pack_p(p1, 8);
; }
; __device__ __forceinline__ void att_exp_pack(fa::f32x16& p0, fa::f32x16& p1, float nm, float& lsum, bf16x8 (&pf)[4]) {
;     float ps = 0.f, ps2 = 0.f;
; #pragma unroll
;     for (int r = 0; r < 16; ++r) { p0[r] = __builtin_amdgcn_exp2f(vadd1(p0[r], nm)); p1[r] = __builtin_amdgcn_exp2f(vadd1(p1[r], nm)); ps += p0[r]; ps += p1[r]; }
;     lsum += ps + ps2;
;     pf[0] = fa::pack_p(p0, 0); pf[1] = fa::pack_p(p0, 8); pf[2] = fa::pack_p(p1, 0); pf[3] = fa::pack_p(p1, 8);
; }
	v_and_b32_e32 v116, 64, v1
	v_xor_b32_e32 v115, 32, v1
	v_add_u32_e32 v116, 64, v116
	v_cmp_lt_i32_e32 vcc, v115, v116
	s_nop 1
	v_cndmask_b32_e32 v115, v1, v115, vcc
	v_lshlrev_b32_e32 v115, 2, v115
	ds_bpermute_b32 v115, v115, v114
	v_max_f32_e32 v114, v114, v114
	s_waitcnt lgkmcnt(0)
	v_max_f32_e32 v115, v115, v115
	v_max_f32_e32 v114, v114, v115
	v_max_f32_e32 v115, 0, v114
	v_exp_f32_e64 v114, -v115
	v_add_f32_e32 v131, v131, v115
	v_mul_f32_e32 v220, v220, v114
	v_pk_mul_f32 v[96:97], v[96:97], v[114:115] op_sel_hi:[1,0]
	v_pk_mul_f32 v[94:95], v[94:95], v[114:115] op_sel_hi:[1,0]
	v_pk_mul_f32 v[92:93], v[92:93], v[114:115] op_sel_hi:[1,0]
	v_pk_mul_f32 v[90:91], v[90:91], v[114:115] op_sel_hi:[1,0]
	v_pk_mul_f32 v[88:89], v[88:89], v[114:115] op_sel_hi:[1,0]
	v_pk_mul_f32 v[86:87], v[86:87], v[114:115] op_sel_hi:[1,0]
	v_pk_mul_f32 v[84:85], v[84:85], v[114:115] op_sel_hi:[1,0]
	v_pk_mul_f32 v[82:83], v[82:83], v[114:115] op_sel_hi:[1,0]
	v_pk_mul_f32 v[80:81], v[80:81], v[114:115] op_sel_hi:[1,0]
	v_pk_mul_f32 v[78:79], v[78:79], v[114:115] op_sel_hi:[1,0]
	v_pk_mul_f32 v[76:77], v[76:77], v[114:115] op_sel_hi:[1,0]
	v_pk_mul_f32 v[74:75], v[74:75], v[114:115] op_sel_hi:[1,0]
	v_pk_mul_f32 v[72:73], v[72:73], v[114:115] op_sel_hi:[1,0]
	v_pk_mul_f32 v[70:71], v[70:71], v[114:115] op_sel_hi:[1,0]
	v_pk_mul_f32 v[68:69], v[68:69], v[114:115] op_sel_hi:[1,0]
	v_pk_mul_f32 v[66:67], v[66:67], v[114:115] op_sel_hi:[1,0]
	v_sub_f32_e32 v34, v34, v115
	v_sub_f32_e32 v35, v35, v115
	v_sub_f32_e32 v36, v36, v115
	v_sub_f32_e32 v37, v37, v115
	v_sub_f32_e32 v38, v38, v115
	v_sub_f32_e32 v39, v39, v115
	v_sub_f32_e32 v40, v40, v115
	v_sub_f32_e32 v41, v41, v115
	v_sub_f32_e32 v42, v42, v115
	v_sub_f32_e32 v43, v43, v115
	v_sub_f32_e32 v44, v44, v115
	v_sub_f32_e32 v45, v45, v115
	v_sub_f32_e32 v46, v46, v115
	v_sub_f32_e32 v47, v47, v115
	v_sub_f32_e32 v48, v48, v115
	v_sub_f32_e32 v49, v49, v115
	v_sub_f32_e32 v50, v50, v115
	v_sub_f32_e32 v51, v51, v115
	v_sub_f32_e32 v52, v52, v115
	v_sub_f32_e32 v53, v53, v115
	v_sub_f32_e32 v54, v54, v115
	v_sub_f32_e32 v55, v55, v115
	v_sub_f32_e32 v56, v56, v115
	v_sub_f32_e32 v57, v57, v115
	v_sub_f32_e32 v58, v58, v115
	v_sub_f32_e32 v59, v59, v115
	v_sub_f32_e32 v60, v60, v115
	v_sub_f32_e32 v61, v61, v115
	v_sub_f32_e32 v62, v62, v115
	v_sub_f32_e32 v63, v63, v115
	v_sub_f32_e32 v64, v64, v115
	v_sub_f32_e32 v65, v65, v115
	v_sub_f32_e32 v232, v232, v115
	v_sub_f32_e32 v233, v233, v115
	v_sub_f32_e32 v234, v234, v115
	v_sub_f32_e32 v235, v235, v115
	v_sub_f32_e32 v236, v236, v115
	v_sub_f32_e32 v237, v237, v115
	v_sub_f32_e32 v238, v238, v115
	v_sub_f32_e32 v239, v239, v115
	v_sub_f32_e32 v240, v240, v115
	v_sub_f32_e32 v241, v241, v115
	v_sub_f32_e32 v242, v242, v115
	v_sub_f32_e32 v243, v243, v115
	v_sub_f32_e32 v244, v244, v115
	v_sub_f32_e32 v245, v245, v115
	v_sub_f32_e32 v246, v246, v115
	v_sub_f32_e32 v247, v247, v115
.LBB0_2993:
	s_mov_b64 s[8:9], -1
	s_and_b64 vcc, exec, s[12:13]
	s_barrier
	s_cbranch_vccz .LBB0_2995
	v_exp_f32_e32 v114, v34
	v_exp_f32_e32 v115, v50
	v_exp_f32_e32 v117, v35
	v_exp_f32_e32 v118, v51
	v_exp_f32_e32 v119, v36
	v_exp_f32_e32 v120, v52
	v_exp_f32_e32 v121, v37
	v_exp_f32_e32 v122, v53
	v_pk_add_f32 v[252:253], v[114:115], v[118:119]
	v_exp_f32_e32 v123, v38
	v_exp_f32_e32 v124, v54
	v_pk_add_f32 v[252:253], v[252:253], v[120:121]
	v_exp_f32_e32 v125, v39
	v_exp_f32_e32 v126, v55
	v_pk_add_f32 v[252:253], v[252:253], v[122:123]
	v_exp_f32_e32 v127, v40
	v_exp_f32_e32 v128, v56
	v_pk_add_f32 v[252:253], v[252:253], v[124:125]
	v_exp_f32_e32 v129, v41
	v_exp_f32_e32 v98, v57
	v_pk_add_f32 v[252:253], v[252:253], v[126:127]
	v_exp_f32_e32 v99, v42
	v_exp_f32_e32 v100, v58
	v_pk_add_f32 v[252:253], v[252:253], v[128:129]
	v_exp_f32_e32 v101, v43
	v_exp_f32_e32 v102, v59
	v_pk_add_f32 v[252:253], v[252:253], v[98:99]
	v_exp_f32_e32 v103, v44
	v_exp_f32_e32 v104, v60
	v_pk_add_f32 v[252:253], v[252:253], v[100:101]
	v_exp_f32_e32 v105, v45
	v_exp_f32_e32 v106, v61
	v_pk_add_f32 v[252:253], v[252:253], v[102:103]
	v_exp_f32_e32 v107, v46
	v_exp_f32_e32 v108, v62
	v_pk_add_f32 v[252:253], v[252:253], v[104:105]
	v_exp_f32_e32 v109, v47
	v_exp_f32_e32 v110, v63
	v_pk_add_f32 v[252:253], v[252:253], v[106:107]
	v_exp_f32_e32 v111, v48
	v_exp_f32_e32 v112, v64
	v_pk_add_f32 v[252:253], v[252:253], v[108:109]
	v_exp_f32_e32 v113, v49
	v_pk_add_f32 v[252:253], v[252:253], v[110:111]
	v_exp_f32_e32 v173, v65
	v_pk_add_f32 v[252:253], v[252:253], v[112:113]
	v_add_f32_e32 v116, v252, v253
	v_add_f32_e32 v116, v116, v117
	v_cvt_pk_bf16_f32 v224, v114, v117
	v_add_f32_e32 v223, v173, v116
	v_cvt_pk_bf16_f32 v225, v119, v121
	v_cvt_pk_bf16_f32 v226, v123, v125
	v_cvt_pk_bf16_f32 v227, v127, v129
	v_cvt_pk_bf16_f32 v228, v99, v101
	v_cvt_pk_bf16_f32 v229, v103, v105
	v_cvt_pk_bf16_f32 v230, v107, v109
	v_cvt_pk_bf16_f32 v231, v111, v113
	v_cvt_pk_bf16_f32 v166, v115, v118
	v_cvt_pk_bf16_f32 v167, v120, v122
	v_cvt_pk_bf16_f32 v168, v124, v126
	v_cvt_pk_bf16_f32 v169, v128, v98
	v_cvt_pk_bf16_f32 v170, v100, v102
	v_cvt_pk_bf16_f32 v171, v104, v106
	v_cvt_pk_bf16_f32 v172, v108, v110
	v_cvt_pk_bf16_f32 v173, v112, v173
	ds_read_b64_tr_b16 v[114:115], v221 offset:34816
	ds_read_b64_tr_b16 v[116:117], v221 offset:35328
	ds_read_b64_tr_b16 v[174:175], v221 offset:38912
	ds_read_b64_tr_b16 v[176:177], v221 offset:39424
	s_waitcnt lgkmcnt(2)
	v_mfma_f32_32x32x16_bf16 v[82:97], v[114:117], v[224:227], v[82:97]
	s_mov_b64 s[8:9], 0
	s_waitcnt lgkmcnt(0)
	v_mfma_f32_32x32x16_bf16 v[66:81], v[174:177], v[224:227], v[66:81]
	ds_read_b64_tr_b16 v[224:225], v221 offset:35840
	ds_read_b64_tr_b16 v[226:227], v221 offset:36352
	ds_read_b64_tr_b16 v[174:175], v221 offset:39936
	ds_read_b64_tr_b16 v[176:177], v221 offset:40448
	s_waitcnt lgkmcnt(2)
	v_mfma_f32_32x32x16_bf16 v[82:97], v[224:227], v[228:231], v[82:97]
	s_waitcnt lgkmcnt(0)
	v_mfma_f32_32x32x16_bf16 v[66:81], v[174:177], v[228:231], v[66:81]
	ds_read_b64_tr_b16 v[224:225], v221 offset:36864
	ds_read_b64_tr_b16 v[226:227], v221 offset:37376
	ds_read_b64_tr_b16 v[228:229], v221 offset:40960
	ds_read_b64_tr_b16 v[230:231], v221 offset:41472
	s_waitcnt lgkmcnt(2)
	v_mfma_f32_32x32x16_bf16 v[82:97], v[224:227], v[166:169], v[82:97]
	s_waitcnt lgkmcnt(0)
	v_mfma_f32_32x32x16_bf16 v[66:81], v[228:231], v[166:169], v[66:81]
	ds_read_b64_tr_b16 v[224:225], v221 offset:37888
	ds_read_b64_tr_b16 v[226:227], v221 offset:38400
	ds_read_b64_tr_b16 v[228:229], v221 offset:41984
	ds_read_b64_tr_b16 v[230:231], v221 offset:42496
	s_waitcnt lgkmcnt(2)
	v_mfma_f32_32x32x16_bf16 v[82:97], v[224:227], v[170:173], v[82:97]
	s_waitcnt lgkmcnt(0)
	v_mfma_f32_32x32x16_bf16 v[66:81], v[228:231], v[170:173], v[66:81]
; #define LAS __attribute__((address_space(3)))
; __device__ __forceinline__ void att_qk_exp(const LAS char* kb, const bf16x8 (&qf)[6], float nm, fa::f32x16& n0, fa::f32x16& n1, fa::f32x16& p0, fa::f32x16& p1, float& lsum, bf16x8 (&pf)[4]) {
;     const fa::f32x16 zero = {0.f, 0.f, 0.f, 0.f, 0.f, 0.f, 0.f, 0.f, 0.f, 0.f, 0.f, 0.f, 0.f, 0.f, 0.f, 0.f};
;     bf16x8 kc0 = *(const LAS bf16x8*)kb, kc1 = *(const LAS bf16x8*)(kb + 32 * fa::KP_A);
;     float ps = 0.f, ps2 = 0.f;
; #pragma unroll
;     for (int st = 0; st < 6; ++st) {
;         bf16x8 kn0 = kc0, kn1 = kc1;
;         if (st < 5) { kn0 = *(const LAS bf16x8*)(kb + 32 * (st + 1)); kn1 = *(const LAS bf16x8*)(kb + 32 * fa::KP_A + 32 * (st + 1)); }
;         n0 = __builtin_amdgcn_mfma_f32_32x32x16_bf16(kc0, qf[st], st == 0 ? zero : n0, 0, 0, 0);
;         n1 = __builtin_amdgcn_mfma_f32_32x32x16_bf16(kc1, qf[st], st == 0 ? zero : n1, 0, 0, 0);
;         constexpr int lo[7] = {0, 2, 6, 8, 10, 14, 16};
; #pragma unroll
;         for (int r = lo[st]; r < lo[st + 1]; ++r) {
;             p0[r] = __builtin_amdgcn_exp2f(vadd1(p0[r], nm)); p1[r] = __builtin_amdgcn_exp2f(vadd1(p1[r], nm));
;             ps += p0[r]; ps += p1[r]; }
;         kc0 = kn0; kc1 = kn1;
;         __builtin_amdgcn_sched_barrier(0);
;     }
;     lsum += ps + ps2;
;     pf[0] = fa::pack_p(p0, 0); pf[1] = fa::pack_p(p0, 8); pf[2] = fa::pack_p(p1, 0); pf[3] = fa::pack_p(p1, 8);
; }
; __device__ __forceinline__ void att_exp_pack(fa::f32x16& p0, fa::f32x16& p1, float nm, float& lsum, bf16x8 (&pf)[4]) {
;     float ps = 0.f, ps2 = 0.f;
; #pragma unroll
;     for (int r = 0; r < 16; ++r) { p0[r] = __builtin_amdgcn_exp2f(vadd1(p0[r], nm)); p1[r] = __builtin_amdgcn_exp2f(vadd1(p1[r], nm)); ps += p0[r]; ps += p1[r]; }
;     lsum += ps + ps2;
;     pf[0] = fa::pack_p(p0, 0); pf[1] = fa::pack_p(p0, 8); pf[2] = fa::pack_p(p1, 0); pf[3] = fa::pack_p(p1, 8);
; }
; __device__ __forceinline__ float att_pv_max(fa::f32x16& o0, fa::f32x16& o1, const LAS char* vb, const bf16x8 (&pf)[4], const fa::f32x16& n0, const fa::f32x16& n1) {
;     using namespace fa;
;     float ta = n0[0], tb = n1[0];
;     s16x4 a0 = vtr(vb), a1 = vtr(vb + 512), b0 = vtr(vb + 4096), b1 = vtr(vb + 4096 + 512);
; #pragma unroll
;     for (int ks = 0; ks < 4; ++ks) {
;         s16x4 na0 = a0, na1 = a1, nb0 = b0, nb1 = b1;
.LBB0_2995:
	s_andn2_b64 vcc, exec, s[8:9]
	s_cbranch_vccnz .LBB0_2997
	v_add_u32_e32 v98, s19, v218
	ds_read_b128 v[2:5], v98
	ds_read_b128 v[18:21], v98 offset:6656
	ds_read_b128 v[114:117], v98 offset:32
	ds_read_b128 v[118:121], v98 offset:6688
	v_exp_f32_e32 v99, v34
	v_exp_f32_e32 v100, v50
	s_waitcnt lgkmcnt(3)
	v_mfma_f32_32x32x16_bf16 v[2:17], v[2:5], v[134:137], v[232:247]
	v_exp_f32_e32 v101, v35
	v_exp_f32_e32 v102, v51
	s_waitcnt lgkmcnt(2)
	v_mfma_f32_32x32x16_bf16 v[18:33], v[18:21], v[134:137], v[232:247]
	s_waitcnt lgkmcnt(1)
	v_mfma_f32_32x32x16_bf16 v[2:17], v[114:117], v[138:141], v[2:17]
	v_exp_f32_e32 v103, v36
	ds_read_b128 v[122:125], v98 offset:64
	ds_read_b128 v[126:129], v98 offset:6720
	v_exp_f32_e32 v104, v52
	v_exp_f32_e32 v114, v37
	s_waitcnt lgkmcnt(2)
	v_mfma_f32_32x32x16_bf16 v[18:33], v[118:121], v[138:141], v[18:33]
	v_exp_f32_e32 v115, v53
	v_exp_f32_e32 v116, v38
	v_exp_f32_e32 v117, v54
	v_exp_f32_e32 v105, v39
	v_exp_f32_e32 v106, v55
	s_waitcnt lgkmcnt(1)
	v_mfma_f32_32x32x16_bf16 v[2:17], v[122:125], v[142:145], v[2:17]
	ds_read_b128 v[34:37], v98 offset:96
	ds_read_b128 v[50:53], v98 offset:6752
	v_exp_f32_e32 v118, v40
	v_exp_f32_e32 v119, v56
	s_waitcnt lgkmcnt(2)
	v_mfma_f32_32x32x16_bf16 v[18:33], v[126:129], v[142:145], v[18:33]
	v_exp_f32_e32 v120, v41
	v_exp_f32_e32 v121, v57
	s_waitcnt lgkmcnt(1)
	v_mfma_f32_32x32x16_bf16 v[2:17], v[34:37], v[146:149], v[2:17]
	ds_read_b128 v[38:41], v98 offset:128
	ds_read_b128 v[54:57], v98 offset:6784
	v_exp_f32_e32 v42, v42
	v_exp_f32_e32 v58, v58
	s_waitcnt lgkmcnt(2)
	v_mfma_f32_32x32x16_bf16 v[18:33], v[50:53], v[146:149], v[18:33]
	v_exp_f32_e32 v43, v43
	v_exp_f32_e32 v59, v59
	s_waitcnt lgkmcnt(1)
	v_mfma_f32_32x32x16_bf16 v[2:17], v[38:41], v[150:153], v[2:17]
	ds_read_b128 v[34:37], v98 offset:160
	ds_read_b128 v[50:53], v98 offset:6816
	v_exp_f32_e32 v39, v45
	s_waitcnt lgkmcnt(2)
	v_mfma_f32_32x32x16_bf16 v[18:33], v[54:57], v[150:153], v[18:33]
	v_exp_f32_e32 v61, v61
	v_exp_f32_e32 v44, v44
	v_exp_f32_e32 v40, v46
	v_exp_f32_e32 v60, v60
	v_exp_f32_e32 v62, v62
	v_exp_f32_e32 v41, v47
	v_exp_f32_e32 v63, v63
	s_waitcnt lgkmcnt(1)
	v_mfma_f32_32x32x16_bf16 v[2:17], v[34:37], v[154:157], v[2:17]
	v_exp_f32_e32 v45, v48
	v_exp_f32_e32 v54, v64
	v_mov_b32_e32 v38, v49
	v_exp_f32_e32 v49, v65
	v_pk_add_f32 v[250:251], v[100:101], v[102:103]
	v_pk_add_f32 v[250:251], v[250:251], v[114:115]
	v_pk_add_f32 v[250:251], v[250:251], v[116:117]
	v_pk_add_f32 v[250:251], v[250:251], v[104:105]
	v_pk_add_f32 v[250:251], v[250:251], v[118:119]
	v_pk_add_f32 v[250:251], v[250:251], v[120:121]
	v_pk_add_f32 v[250:251], v[250:251], v[42:43]
	v_pk_add_f32 v[250:251], v[250:251], v[58:59]
	v_pk_add_f32 v[250:251], v[250:251], v[60:61]
	s_waitcnt lgkmcnt(0)
	v_mfma_f32_32x32x16_bf16 v[18:33], v[50:53], v[154:157], v[18:33]
	v_exp_f32_e32 v46, v38
	v_pk_add_f32 v[250:251], v[250:251], v[40:41]
	v_pk_add_f32 v[250:251], v[250:251], v[62:63]
	v_pk_add_f32 v[250:251], v[250:251], v[44:45]
	v_add_f32_e32 v34, v250, v251
	v_add_f32_e32 v34, v34, v39
	v_add_f32_e32 v34, v34, v46
	v_add_f32_e32 v34, v34, v54
	v_add_f32_e32 v34, v34, v99
	v_add_f32_e32 v34, v34, v106
	v_add_f32_e32 v223, v49, v34
	v_cvt_pk_bf16_f32 v34, v99, v101
	v_cvt_pk_bf16_f32 v35, v103, v114
	v_cvt_pk_bf16_f32 v36, v116, v105
	v_cvt_pk_bf16_f32 v37, v118, v120
	v_cvt_pk_bf16_f32 v38, v42, v43
	v_cvt_pk_bf16_f32 v39, v44, v39
	v_cvt_pk_bf16_f32 v40, v40, v41
	v_cvt_pk_bf16_f32 v41, v45, v46
	v_cvt_pk_bf16_f32 v42, v100, v102
	v_cvt_pk_bf16_f32 v43, v104, v115
	v_cvt_pk_bf16_f32 v44, v117, v106
	v_cvt_pk_bf16_f32 v45, v119, v121
	v_cvt_pk_bf16_f32 v46, v58, v59
	v_cvt_pk_bf16_f32 v47, v60, v61
	v_cvt_pk_bf16_f32 v48, v62, v63
	v_cvt_pk_bf16_f32 v49, v54, v49
	ds_read_b64_tr_b16 v[50:51], v221 offset:34816
	ds_read_b64_tr_b16 v[52:53], v221 offset:35328
	ds_read_b64_tr_b16 v[54:55], v221 offset:35840
	ds_read_b64_tr_b16 v[56:57], v221 offset:36352
	s_waitcnt lgkmcnt(2)
	v_mfma_f32_32x32x16_bf16 v[82:97], v[50:53], v[34:37], v[82:97]
	ds_read_b64_tr_b16 v[50:51], v221 offset:38912
	ds_read_b64_tr_b16 v[52:53], v221 offset:39424
	ds_read_b64_tr_b16 v[58:59], v221 offset:39936
	ds_read_b64_tr_b16 v[60:61], v221 offset:40448
	s_waitcnt lgkmcnt(2)
	v_mfma_f32_32x32x16_bf16 v[66:81], v[50:53], v[34:37], v[66:81]
	ds_read_b64_tr_b16 v[34:35], v221 offset:36864
	ds_read_b64_tr_b16 v[36:37], v221 offset:37376
	ds_read_b64_tr_b16 v[50:51], v221 offset:40960
	ds_read_b64_tr_b16 v[52:53], v221 offset:41472
	v_mfma_f32_32x32x16_bf16 v[82:97], v[54:57], v[38:41], v[82:97]
	s_waitcnt lgkmcnt(4)
	v_mfma_f32_32x32x16_bf16 v[66:81], v[58:61], v[38:41], v[66:81]
	s_waitcnt lgkmcnt(2)
	v_mfma_f32_32x32x16_bf16 v[82:97], v[34:37], v[42:45], v[82:97]
	ds_read_b64_tr_b16 v[34:35], v221 offset:37888
	ds_read_b64_tr_b16 v[36:37], v221 offset:38400
	ds_read_b64_tr_b16 v[38:39], v221 offset:41984
	ds_read_b64_tr_b16 v[40:41], v221 offset:42496
	s_waitcnt lgkmcnt(4)
	v_mfma_f32_32x32x16_bf16 v[66:81], v[50:53], v[42:45], v[66:81]
	v_max_f32_e32 v42, v19, v19
	v_max_f32_e32 v43, v18, v18
	v_max_f32_e32 v42, v43, v42
	v_max3_f32 v42, v42, v20, v21
	s_waitcnt lgkmcnt(2)
	v_mfma_f32_32x32x16_bf16 v[82:97], v[34:37], v[46:49], v[82:97]
	v_max3_f32 v35, v2, v3, v4
	v_max3_f32 v42, v42, v22, v23
	v_max3_f32 v35, v35, v5, v6
	v_max3_f32 v42, v42, v24, v25
	v_max3_f32 v35, v35, v7, v8
	v_max3_f32 v34, v42, v26, v27
	v_max3_f32 v35, v35, v9, v10
	v_max3_f32 v34, v34, v28, v29
	v_max3_f32 v35, v35, v11, v12
	v_max3_f32 v35, v35, v13, v14
	v_max3_f32 v34, v34, v30, v31
	s_waitcnt lgkmcnt(0)
	v_mfma_f32_32x32x16_bf16 v[66:81], v[38:41], v[46:49], v[66:81]
	v_max3_f32 v35, v35, v15, v16
	v_max3_f32 v34, v34, v32, v33
	v_max3_f32 v201, v35, v17, v34
